# epilogue de-serialisation: batched residual x-stream (out+down phases, counted waits) and phase-0 transpose loads issued 8-at-a-time
# speedup vs baseline: 1.0382x; 1.0142x over previous
.LBB0_93:
	s_bitset1_b32 s15, 7
	s_waitcnt lgkmcnt(0)
	s_barrier
	v_add_u32_e32 v0, s15, v188
	v_ashrrev_i32_e32 v1, 31, v0
	v_lshlrev_b64 v[0:1], 12, v[0:1]
	v_lshl_add_u64 v[2:3], v[128:129], 0, v[0:1]
	global_load_dwordx4 v[18:21], v[2:3], off
	v_add_u32_e32 v0, s15, v189
	v_ashrrev_i32_e32 v1, 31, v0
	v_lshlrev_b64 v[0:1], 12, v[0:1]
	v_lshl_add_u64 v[4:5], v[128:129], 0, v[0:1]
	global_load_dwordx4 v[22:25], v[4:5], off
	v_add_u32_e32 v0, s15, v191
	v_ashrrev_i32_e32 v1, 31, v0
	v_lshlrev_b64 v[0:1], 12, v[0:1]
	v_lshl_add_u64 v[6:7], v[128:129], 0, v[0:1]
	global_load_dwordx4 v[26:29], v[6:7], off
	v_add_u32_e32 v0, s15, v192
	v_ashrrev_i32_e32 v1, 31, v0
	v_lshlrev_b64 v[0:1], 12, v[0:1]
	v_lshl_add_u64 v[8:9], v[128:129], 0, v[0:1]
	global_load_dwordx4 v[30:33], v[8:9], off
	v_add_u32_e32 v0, s15, v197
	v_ashrrev_i32_e32 v1, 31, v0
	v_lshlrev_b64 v[0:1], 12, v[0:1]
	v_lshl_add_u64 v[10:11], v[128:129], 0, v[0:1]
	global_load_dwordx4 v[34:37], v[10:11], off
	v_add_u32_e32 v0, s15, v198
	v_ashrrev_i32_e32 v1, 31, v0
	v_lshlrev_b64 v[0:1], 12, v[0:1]
	v_lshl_add_u64 v[12:13], v[128:129], 0, v[0:1]
	global_load_dwordx4 v[38:41], v[12:13], off
	v_add_u32_e32 v0, s15, v199
	v_ashrrev_i32_e32 v1, 31, v0
	v_lshlrev_b64 v[0:1], 12, v[0:1]
	v_lshl_add_u64 v[14:15], v[128:129], 0, v[0:1]
	global_load_dwordx4 v[42:45], v[14:15], off
	v_add_u32_e32 v0, s15, v200
	v_ashrrev_i32_e32 v1, 31, v0
	v_lshlrev_b64 v[0:1], 12, v[0:1]
	v_lshl_add_u64 v[16:17], v[128:129], 0, v[0:1]
	global_load_dwordx4 v[46:49], v[16:17], off
	ds_read_b128 v[50:53], v217
	ds_read_b128 v[54:57], v221
	ds_read_b128 v[58:61], v225
	ds_read_b128 v[62:65], v229
	ds_read_b128 v[66:69], v233
	ds_read_b128 v[70:73], v238
	ds_read_b128 v[74:77], v241
	ds_read_b128 v[78:81], v242
	s_waitcnt vmcnt(7) lgkmcnt(7)
	v_pk_add_f32 v[50:51], v[50:51], v[18:19]
	v_pk_add_f32 v[52:53], v[52:53], v[20:21]
	global_store_dwordx4 v[2:3], v[50:53], off
	s_waitcnt vmcnt(7) lgkmcnt(6)
	v_pk_add_f32 v[54:55], v[54:55], v[22:23]
	v_pk_add_f32 v[56:57], v[56:57], v[24:25]
	global_store_dwordx4 v[4:5], v[54:57], off
	s_waitcnt vmcnt(7) lgkmcnt(5)
	v_pk_add_f32 v[58:59], v[58:59], v[26:27]
	v_pk_add_f32 v[60:61], v[60:61], v[28:29]
	global_store_dwordx4 v[6:7], v[58:61], off
	s_waitcnt vmcnt(7) lgkmcnt(4)
	v_pk_add_f32 v[62:63], v[62:63], v[30:31]
	v_pk_add_f32 v[64:65], v[64:65], v[32:33]
	global_store_dwordx4 v[8:9], v[62:65], off
	s_waitcnt vmcnt(7) lgkmcnt(3)
	v_pk_add_f32 v[66:67], v[66:67], v[34:35]
	v_pk_add_f32 v[68:69], v[68:69], v[36:37]
	global_store_dwordx4 v[10:11], v[66:69], off
	s_waitcnt vmcnt(7) lgkmcnt(2)
	v_pk_add_f32 v[70:71], v[70:71], v[38:39]
	v_pk_add_f32 v[72:73], v[72:73], v[40:41]
	global_store_dwordx4 v[12:13], v[70:73], off
	s_waitcnt vmcnt(7) lgkmcnt(1)
	v_pk_add_f32 v[74:75], v[74:75], v[42:43]
	v_pk_add_f32 v[76:77], v[76:77], v[44:45]
	global_store_dwordx4 v[14:15], v[74:77], off
	s_waitcnt vmcnt(7) lgkmcnt(0)
	v_pk_add_f32 v[78:79], v[78:79], v[46:47]
	v_pk_add_f32 v[80:81], v[80:81], v[48:49]
	global_store_dwordx4 v[16:17], v[78:81], off
	v_add_u32_e32 v0, s15, v201
	v_ashrrev_i32_e32 v1, 31, v0
	v_lshlrev_b64 v[0:1], 12, v[0:1]
	v_lshl_add_u64 v[2:3], v[128:129], 0, v[0:1]
	global_load_dwordx4 v[18:21], v[2:3], off
	v_add_u32_e32 v0, s15, v205
	v_ashrrev_i32_e32 v1, 31, v0
	v_lshlrev_b64 v[0:1], 12, v[0:1]
	v_lshl_add_u64 v[4:5], v[128:129], 0, v[0:1]
	global_load_dwordx4 v[22:25], v[4:5], off
	v_add_u32_e32 v0, s15, v206
	v_ashrrev_i32_e32 v1, 31, v0
	v_lshlrev_b64 v[0:1], 12, v[0:1]
	v_lshl_add_u64 v[6:7], v[128:129], 0, v[0:1]
	global_load_dwordx4 v[26:29], v[6:7], off
	v_add_u32_e32 v0, s15, v207
	v_ashrrev_i32_e32 v1, 31, v0
	v_lshlrev_b64 v[0:1], 12, v[0:1]
	v_lshl_add_u64 v[8:9], v[128:129], 0, v[0:1]
	global_load_dwordx4 v[30:33], v[8:9], off
	v_add_u32_e32 v0, s15, v208
	v_ashrrev_i32_e32 v1, 31, v0
	v_lshlrev_b64 v[0:1], 12, v[0:1]
	v_lshl_add_u64 v[10:11], v[128:129], 0, v[0:1]
	global_load_dwordx4 v[34:37], v[10:11], off
	v_add_u32_e32 v0, s15, v209
	v_ashrrev_i32_e32 v1, 31, v0
	v_lshlrev_b64 v[0:1], 12, v[0:1]
	v_lshl_add_u64 v[12:13], v[128:129], 0, v[0:1]
	global_load_dwordx4 v[38:41], v[12:13], off
	v_add_u32_e32 v0, s15, v210
	v_ashrrev_i32_e32 v1, 31, v0
	v_lshlrev_b64 v[0:1], 12, v[0:1]
	v_lshl_add_u64 v[14:15], v[128:129], 0, v[0:1]
	global_load_dwordx4 v[42:45], v[14:15], off
	v_add_u32_e32 v0, s15, v213
	v_ashrrev_i32_e32 v1, 31, v0
	v_lshlrev_b64 v[0:1], 12, v[0:1]
	v_lshl_add_u64 v[16:17], v[128:129], 0, v[0:1]
	global_load_dwordx4 v[46:49], v[16:17], off
	ds_read_b128 v[50:53], v243
	ds_read_b128 v[54:57], v244
	ds_read_b128 v[58:61], v245
	ds_read_b128 v[62:65], v246
	ds_read_b128 v[66:69], v247
	ds_read_b128 v[70:73], v248
	ds_read_b128 v[74:77], v249
	ds_read_b128 v[78:81], v250
	s_waitcnt vmcnt(7) lgkmcnt(7)
	v_pk_add_f32 v[50:51], v[50:51], v[18:19]
	v_pk_add_f32 v[52:53], v[52:53], v[20:21]
	global_store_dwordx4 v[2:3], v[50:53], off
	s_waitcnt vmcnt(7) lgkmcnt(6)
	v_pk_add_f32 v[54:55], v[54:55], v[22:23]
	v_pk_add_f32 v[56:57], v[56:57], v[24:25]
	global_store_dwordx4 v[4:5], v[54:57], off
	s_waitcnt vmcnt(7) lgkmcnt(5)
	v_pk_add_f32 v[58:59], v[58:59], v[26:27]
	v_pk_add_f32 v[60:61], v[60:61], v[28:29]
	global_store_dwordx4 v[6:7], v[58:61], off
	s_waitcnt vmcnt(7) lgkmcnt(4)
	v_pk_add_f32 v[62:63], v[62:63], v[30:31]
	v_pk_add_f32 v[64:65], v[64:65], v[32:33]
	global_store_dwordx4 v[8:9], v[62:65], off
	s_waitcnt vmcnt(7) lgkmcnt(3)
	v_pk_add_f32 v[66:67], v[66:67], v[34:35]
	v_pk_add_f32 v[68:69], v[68:69], v[36:37]
	global_store_dwordx4 v[10:11], v[66:69], off
	s_waitcnt vmcnt(7) lgkmcnt(2)
	v_pk_add_f32 v[70:71], v[70:71], v[38:39]
	v_pk_add_f32 v[72:73], v[72:73], v[40:41]
	global_store_dwordx4 v[12:13], v[70:73], off
	s_waitcnt vmcnt(7) lgkmcnt(1)
	v_pk_add_f32 v[74:75], v[74:75], v[42:43]
	v_pk_add_f32 v[76:77], v[76:77], v[44:45]
	global_store_dwordx4 v[14:15], v[74:77], off
	s_waitcnt vmcnt(7) lgkmcnt(0)
	v_pk_add_f32 v[78:79], v[78:79], v[46:47]
	v_pk_add_f32 v[80:81], v[80:81], v[48:49]
	global_store_dwordx4 v[16:17], v[78:81], off
	s_add_i32 s10, s10, s13
	s_add_i32 s11, s11, s12
	s_cmpk_gt_u32 s10, 0x4ff
	s_barrier
	s_cbranch_scc1 .LBB0_111

.LBB0_108:
	s_ashr_i32 s5, s4, 31
	v_lshl_add_u64 v[128:129], s[4:5], 2, v[178:179]
	s_waitcnt vmcnt(0) lgkmcnt(0)
	s_barrier
	v_add_u32_e32 v130, s15, v188
	v_ashrrev_i32_e32 v131, 31, v130
	v_lshlrev_b64 v[130:131], 12, v[130:131]
	v_lshl_add_u64 v[132:133], v[128:129], 0, v[130:131]
	global_load_dwordx4 v[140:143], v[132:133], off
	v_add_u32_e32 v130, s15, v189
	v_ashrrev_i32_e32 v131, 31, v130
	v_lshlrev_b64 v[130:131], 12, v[130:131]
	v_lshl_add_u64 v[134:135], v[128:129], 0, v[130:131]
	global_load_dwordx4 v[144:147], v[134:135], off
	v_add_u32_e32 v130, s15, v191
	v_ashrrev_i32_e32 v131, 31, v130
	v_lshlrev_b64 v[130:131], 12, v[130:131]
	v_lshl_add_u64 v[136:137], v[128:129], 0, v[130:131]
	global_load_dwordx4 v[148:151], v[136:137], off
	v_add_u32_e32 v130, s15, v192
	v_ashrrev_i32_e32 v131, 31, v130
	v_lshlrev_b64 v[130:131], 12, v[130:131]
	v_lshl_add_u64 v[138:139], v[128:129], 0, v[130:131]
	global_load_dwordx4 v[152:155], v[138:139], off
	ds_read_b128 v[156:159], v217
	ds_read_b128 v[160:163], v221
	ds_read_b128 v[164:167], v225
	ds_read_b128 v[168:171], v229
	s_waitcnt vmcnt(3) lgkmcnt(3)
	v_pk_add_f32 v[156:157], v[156:157], v[140:141]
	v_pk_add_f32 v[158:159], v[158:159], v[142:143]
	global_store_dwordx4 v[132:133], v[156:159], off
	s_waitcnt vmcnt(3) lgkmcnt(2)
	v_pk_add_f32 v[160:161], v[160:161], v[144:145]
	v_pk_add_f32 v[162:163], v[162:163], v[146:147]
	global_store_dwordx4 v[134:135], v[160:163], off
	s_waitcnt vmcnt(3) lgkmcnt(1)
	v_pk_add_f32 v[164:165], v[164:165], v[148:149]
	v_pk_add_f32 v[166:167], v[166:167], v[150:151]
	global_store_dwordx4 v[136:137], v[164:167], off
	s_waitcnt vmcnt(3) lgkmcnt(0)
	v_pk_add_f32 v[168:169], v[168:169], v[152:153]
	v_pk_add_f32 v[170:171], v[170:171], v[154:155]
	global_store_dwordx4 v[138:139], v[168:171], off
	v_add_u32_e32 v130, s15, v197
	v_ashrrev_i32_e32 v131, 31, v130
	v_lshlrev_b64 v[130:131], 12, v[130:131]
	v_lshl_add_u64 v[132:133], v[128:129], 0, v[130:131]
	global_load_dwordx4 v[140:143], v[132:133], off
	v_add_u32_e32 v130, s15, v198
	v_ashrrev_i32_e32 v131, 31, v130
	v_lshlrev_b64 v[130:131], 12, v[130:131]
	v_lshl_add_u64 v[134:135], v[128:129], 0, v[130:131]
	global_load_dwordx4 v[144:147], v[134:135], off
	v_add_u32_e32 v130, s15, v199
	v_ashrrev_i32_e32 v131, 31, v130
	v_lshlrev_b64 v[130:131], 12, v[130:131]
	v_lshl_add_u64 v[136:137], v[128:129], 0, v[130:131]
	global_load_dwordx4 v[148:151], v[136:137], off
	v_add_u32_e32 v130, s15, v200
	v_ashrrev_i32_e32 v131, 31, v130
	v_lshlrev_b64 v[130:131], 12, v[130:131]
	v_lshl_add_u64 v[138:139], v[128:129], 0, v[130:131]
	global_load_dwordx4 v[152:155], v[138:139], off
	ds_read_b128 v[156:159], v233
	ds_read_b128 v[160:163], v238
	ds_read_b128 v[164:167], v241
	ds_read_b128 v[168:171], v242
	s_waitcnt vmcnt(3) lgkmcnt(3)
	v_pk_add_f32 v[156:157], v[156:157], v[140:141]
	v_pk_add_f32 v[158:159], v[158:159], v[142:143]
	global_store_dwordx4 v[132:133], v[156:159], off
	s_waitcnt vmcnt(3) lgkmcnt(2)
	v_pk_add_f32 v[160:161], v[160:161], v[144:145]
	v_pk_add_f32 v[162:163], v[162:163], v[146:147]
	global_store_dwordx4 v[134:135], v[160:163], off
	s_waitcnt vmcnt(3) lgkmcnt(1)
	v_pk_add_f32 v[164:165], v[164:165], v[148:149]
	v_pk_add_f32 v[166:167], v[166:167], v[150:151]
	global_store_dwordx4 v[136:137], v[164:167], off
	s_waitcnt vmcnt(3) lgkmcnt(0)
	v_pk_add_f32 v[168:169], v[168:169], v[152:153]
	v_pk_add_f32 v[170:171], v[170:171], v[154:155]
	global_store_dwordx4 v[138:139], v[168:171], off
	v_add_u32_e32 v130, s15, v201
	v_ashrrev_i32_e32 v131, 31, v130
	v_lshlrev_b64 v[130:131], 12, v[130:131]
	v_lshl_add_u64 v[132:133], v[128:129], 0, v[130:131]
	global_load_dwordx4 v[140:143], v[132:133], off
	v_add_u32_e32 v130, s15, v205
	v_ashrrev_i32_e32 v131, 31, v130
	v_lshlrev_b64 v[130:131], 12, v[130:131]
	v_lshl_add_u64 v[134:135], v[128:129], 0, v[130:131]
	global_load_dwordx4 v[144:147], v[134:135], off
	v_add_u32_e32 v130, s15, v206
	v_ashrrev_i32_e32 v131, 31, v130
	v_lshlrev_b64 v[130:131], 12, v[130:131]
	v_lshl_add_u64 v[136:137], v[128:129], 0, v[130:131]
	global_load_dwordx4 v[148:151], v[136:137], off
	v_add_u32_e32 v130, s15, v207
	v_ashrrev_i32_e32 v131, 31, v130
	v_lshlrev_b64 v[130:131], 12, v[130:131]
	v_lshl_add_u64 v[138:139], v[128:129], 0, v[130:131]
	global_load_dwordx4 v[152:155], v[138:139], off
	ds_read_b128 v[156:159], v243
	ds_read_b128 v[160:163], v244
	ds_read_b128 v[164:167], v245
	ds_read_b128 v[168:171], v246
	s_waitcnt vmcnt(3) lgkmcnt(3)
	v_pk_add_f32 v[156:157], v[156:157], v[140:141]
	v_pk_add_f32 v[158:159], v[158:159], v[142:143]
	global_store_dwordx4 v[132:133], v[156:159], off
	s_waitcnt vmcnt(3) lgkmcnt(2)
	v_pk_add_f32 v[160:161], v[160:161], v[144:145]
	v_pk_add_f32 v[162:163], v[162:163], v[146:147]
	global_store_dwordx4 v[134:135], v[160:163], off
	s_waitcnt vmcnt(3) lgkmcnt(1)
	v_pk_add_f32 v[164:165], v[164:165], v[148:149]
	v_pk_add_f32 v[166:167], v[166:167], v[150:151]
	global_store_dwordx4 v[136:137], v[164:167], off
	s_waitcnt vmcnt(3) lgkmcnt(0)
	v_pk_add_f32 v[168:169], v[168:169], v[152:153]
	v_pk_add_f32 v[170:171], v[170:171], v[154:155]
	global_store_dwordx4 v[138:139], v[168:171], off
	v_add_u32_e32 v130, s15, v208
	v_ashrrev_i32_e32 v131, 31, v130
	v_lshlrev_b64 v[130:131], 12, v[130:131]
	v_lshl_add_u64 v[132:133], v[128:129], 0, v[130:131]
	global_load_dwordx4 v[140:143], v[132:133], off
	v_add_u32_e32 v130, s15, v209
	v_ashrrev_i32_e32 v131, 31, v130
	v_lshlrev_b64 v[130:131], 12, v[130:131]
	v_lshl_add_u64 v[134:135], v[128:129], 0, v[130:131]
	global_load_dwordx4 v[144:147], v[134:135], off
	v_add_u32_e32 v130, s15, v210
	v_ashrrev_i32_e32 v131, 31, v130
	v_lshlrev_b64 v[130:131], 12, v[130:131]
	v_lshl_add_u64 v[136:137], v[128:129], 0, v[130:131]
	global_load_dwordx4 v[148:151], v[136:137], off
	v_add_u32_e32 v130, s15, v213
	v_ashrrev_i32_e32 v131, 31, v130
	v_lshlrev_b64 v[130:131], 12, v[130:131]
	v_lshl_add_u64 v[138:139], v[128:129], 0, v[130:131]
	global_load_dwordx4 v[152:155], v[138:139], off
	ds_read_b128 v[156:159], v247
	ds_read_b128 v[160:163], v248
	ds_read_b128 v[164:167], v249
	ds_read_b128 v[168:171], v250
	s_waitcnt vmcnt(3) lgkmcnt(3)
	v_pk_add_f32 v[156:157], v[156:157], v[140:141]
	v_pk_add_f32 v[158:159], v[158:159], v[142:143]
	global_store_dwordx4 v[132:133], v[156:159], off
	s_waitcnt vmcnt(3) lgkmcnt(2)
	v_pk_add_f32 v[160:161], v[160:161], v[144:145]
	v_pk_add_f32 v[162:163], v[162:163], v[146:147]
	global_store_dwordx4 v[134:135], v[160:163], off
	s_waitcnt vmcnt(3) lgkmcnt(1)
	v_pk_add_f32 v[164:165], v[164:165], v[148:149]
	v_pk_add_f32 v[166:167], v[166:167], v[150:151]
	global_store_dwordx4 v[136:137], v[164:167], off
	s_waitcnt vmcnt(3) lgkmcnt(0)
	v_pk_add_f32 v[168:169], v[168:169], v[152:153]
	v_pk_add_f32 v[170:171], v[170:171], v[154:155]
	global_store_dwordx4 v[138:139], v[168:171], off
	s_barrier
	s_nop 0
	v_mov_b32_e32 v130, v190
	s_nop 0
	v_readfirstlane_b32 s4, v130
	s_and_b32 s5, s4, 0xffffff00
	s_cmpk_lg_i32 s5, 0x100
	s_cbranch_scc1 .LBB0_93
	s_and_b32 s4, s4, 0xc0
	v_lshrrev_b32_e32 v131, 3, v130
	v_and_or_b32 v130, v130, 31, s4
	v_and_b32_e32 v131, 4, v131
	v_lshlrev_b32_e32 v130, 2, v130
	v_mad_u32_u24 v132, v131, s33, v130
	ds_write2_b32 v132, v112, v96 offset1:32
	v_add_u32_e32 v96, 0x400, v132
	ds_write2_b32 v96, v113, v97 offset0:4 offset1:36
	v_add_u32_e32 v96, 0x800, v132
	ds_write2_b32 v96, v114, v98 offset0:8 offset1:40
	v_add_u32_e32 v96, 0xc00, v132
	ds_write2_b32 v96, v115, v99 offset0:12 offset1:44
	v_add_u32_e32 v96, 0x2000, v132
	ds_write2_b32 v96, v116, v100 offset0:32 offset1:64
	v_add_u32_e32 v96, 0x2400, v132
	ds_write2_b32 v96, v117, v101 offset0:36 offset1:68
	v_add_u32_e32 v96, 0x2800, v132
	ds_write2_b32 v96, v118, v102 offset0:40 offset1:72
	v_add_u32_e32 v96, 0x2c00, v132
	ds_write2_b32 v96, v119, v103 offset0:44 offset1:76
	v_add_u32_e32 v96, 0x4000, v132
	ds_write2_b32 v96, v120, v104 offset0:64 offset1:96
	v_add_u32_e32 v96, 0x4400, v132
	ds_write2_b32 v96, v121, v105 offset0:68 offset1:100
	v_add_u32_e32 v96, 0x4800, v132
	ds_write2_b32 v96, v122, v106 offset0:72 offset1:104
	v_add_u32_e32 v96, 0x4c00, v132
	ds_write2_b32 v96, v123, v107 offset0:76 offset1:108
	v_add_u32_e32 v96, 0x6000, v132
	ds_write2_b32 v96, v124, v108 offset0:96 offset1:128
	v_add_u32_e32 v96, 0x6400, v132
	ds_write2_b32 v96, v125, v109 offset0:100 offset1:132
	v_add_u32_e32 v96, 0x6800, v132
	ds_write2_b32 v96, v126, v110 offset0:104 offset1:136
	v_add_u32_e32 v96, 0x6c00, v132
	ds_write2_b32 v96, v127, v111 offset0:108 offset1:140
	v_add_u32_e32 v96, 0x8000, v132
	ds_write2_b32 v96, v80, v64 offset0:128 offset1:160
	v_add_u32_e32 v64, 0x8400, v132
	ds_write2_b32 v64, v81, v65 offset0:132 offset1:164
	v_add_u32_e32 v64, 0x8800, v132
	ds_write2_b32 v64, v82, v66 offset0:136 offset1:168
	v_add_u32_e32 v64, 0x8c00, v132
	ds_write2_b32 v64, v83, v67 offset0:140 offset1:172
	v_add_u32_e32 v64, 0xa000, v132
	ds_write2_b32 v64, v84, v68 offset0:160 offset1:192
	v_add_u32_e32 v64, 0xa400, v132
	ds_write2_b32 v64, v85, v69 offset0:164 offset1:196
	v_add_u32_e32 v64, 0xa800, v132
	ds_write2_b32 v64, v86, v70 offset0:168 offset1:200
	v_add_u32_e32 v64, 0xac00, v132
	ds_write2_b32 v64, v87, v71 offset0:172 offset1:204
	v_add_u32_e32 v64, 0xc000, v132
	ds_write2_b32 v64, v88, v72 offset0:192 offset1:224
	v_add_u32_e32 v64, 0xc400, v132
	ds_write2_b32 v64, v89, v73 offset0:196 offset1:228
	v_add_u32_e32 v64, 0xc800, v132
	ds_write2_b32 v64, v90, v74 offset0:200 offset1:232
	v_add_u32_e32 v64, 0xcc00, v132
	ds_write2_b32 v64, v91, v75 offset0:204 offset1:236
	v_add_u32_e32 v64, 0xe200, v132
	ds_write2_b32 v64, v92, v76 offset0:96 offset1:128
	v_add_u32_e32 v64, 0xe600, v132
	ds_write2_b32 v64, v93, v77 offset0:100 offset1:132
	v_add_u32_e32 v64, 0xea00, v132
	ds_write2_b32 v64, v94, v78 offset0:104 offset1:136
	v_add_u32_e32 v64, 0xee00, v132
	ds_write2_b32 v64, v95, v79 offset0:108 offset1:140
	v_mov_b32_e32 v64, 0x10400
	v_mad_u32_u24 v64, v131, s33, v64
	v_add_u32_e32 v65, v130, v64
	ds_write_b32 v65, v48
	v_mov_b32_e32 v48, 0x10810
	v_mad_u32_u24 v48, v131, s33, v48
	v_add_u32_e32 v65, v130, v48
	ds_write_b32 v65, v49
	v_mov_b32_e32 v49, 0x10c20
	v_mad_u32_u24 v49, v131, s33, v49
	v_add_u32_e32 v65, v130, v49
	ds_write_b32 v65, v50
	v_mov_b32_e32 v50, 0x11030
	v_mad_u32_u24 v50, v131, s33, v50
	v_add_u32_e32 v65, v130, v50
	ds_write_b32 v65, v51
	v_mov_b32_e32 v51, 0x12480
	v_mad_u32_u24 v51, v131, s33, v51
	v_add_u32_e32 v65, v130, v51
	ds_write_b32 v65, v52
	v_mov_b32_e32 v52, 0x12890
	v_mad_u32_u24 v52, v131, s33, v52
	v_add_u32_e32 v65, v130, v52
	ds_write_b32 v65, v53
	v_mov_b32_e32 v53, 0x12ca0
	v_mad_u32_u24 v53, v131, s33, v53
	v_add_u32_e32 v65, v130, v53
	ds_write_b32 v65, v54
	v_mov_b32_e32 v54, 0x130b0
	v_mad_u32_u24 v54, v131, s33, v54
	v_add_u32_e32 v65, v130, v54
	ds_write_b32 v65, v55
	v_mov_b32_e32 v55, 0x14500
	v_mad_u32_u24 v55, v131, s33, v55
	v_add_u32_e32 v65, v130, v55
	ds_write_b32 v65, v56
	v_mov_b32_e32 v56, 0x14910
	v_mad_u32_u24 v56, v131, s33, v56
	v_add_u32_e32 v65, v130, v56
	ds_write_b32 v65, v57
	v_mov_b32_e32 v57, 0x14d20
	v_mad_u32_u24 v57, v131, s33, v57
	v_add_u32_e32 v65, v130, v57
	ds_write_b32 v65, v58
	v_mov_b32_e32 v58, 0x15130
	v_mad_u32_u24 v58, v131, s33, v58
	v_add_u32_e32 v65, v130, v58
	ds_write_b32 v65, v59
	v_mov_b32_e32 v59, 0x16580
	v_mad_u32_u24 v59, v131, s33, v59
	v_add_u32_e32 v65, v130, v59
	ds_write_b32 v65, v60
	v_mov_b32_e32 v60, 0x16990
	v_mad_u32_u24 v60, v131, s33, v60
	v_add_u32_e32 v65, v130, v60
	ds_write_b32 v65, v61
	v_mov_b32_e32 v61, 0x16da0
	v_mad_u32_u24 v61, v131, s33, v61
	v_add_u32_e32 v65, v130, v61
	ds_write_b32 v65, v62
	v_mov_b32_e32 v62, 0x171b0
	v_mad_u32_u24 v62, v131, s33, v62
	v_or_b32_e32 v133, 0x80, v130
	v_add_u32_e32 v65, v130, v62
	ds_write_b32 v65, v63
	v_add_u32_e32 v63, v133, v64
	ds_write_b32 v63, v32
	v_add_u32_e32 v32, v133, v48
	ds_write_b32 v32, v33
	v_add_u32_e32 v32, v133, v49
	ds_write_b32 v32, v34
	v_add_u32_e32 v32, v133, v50
	ds_write_b32 v32, v35
	v_add_u32_e32 v32, v133, v51
	ds_write_b32 v32, v36
	v_add_u32_e32 v32, v133, v52
	ds_write_b32 v32, v37
	v_add_u32_e32 v32, v133, v53
	ds_write_b32 v32, v38
	v_add_u32_e32 v32, v133, v54
	ds_write_b32 v32, v39
	v_add_u32_e32 v32, v133, v55
	ds_write_b32 v32, v40
	v_add_u32_e32 v32, v133, v56
	ds_write_b32 v32, v41
	v_add_u32_e32 v32, v133, v57
	ds_write_b32 v32, v42
	v_add_u32_e32 v32, v133, v58
	ds_write_b32 v32, v43
	v_add_u32_e32 v32, v133, v59
	ds_write_b32 v32, v44
	v_add_u32_e32 v32, v133, v60
	ds_write_b32 v32, v45
	v_add_u32_e32 v32, v133, v61
	ds_write_b32 v32, v46
	v_add_u32_e32 v32, v133, v62
	ds_write_b32 v32, v47
	v_mov_b32_e32 v32, 0x18600
	v_mad_u32_u24 v32, v131, s33, v32
	v_add_u32_e32 v33, v130, v32
	ds_write_b32 v33, v16
	v_mov_b32_e32 v16, 0x18a10
	v_mad_u32_u24 v16, v131, s33, v16
	v_add_u32_e32 v33, v130, v16
	ds_write_b32 v33, v17
	v_mov_b32_e32 v17, 0x18e20
	v_mad_u32_u24 v17, v131, s33, v17
	v_add_u32_e32 v33, v130, v17
	ds_write_b32 v33, v18
	v_mov_b32_e32 v18, 0x19230
	v_mad_u32_u24 v18, v131, s33, v18
	v_add_u32_e32 v33, v130, v18
	ds_write_b32 v33, v19
	v_mov_b32_e32 v19, 0x1a680
	v_mad_u32_u24 v19, v131, s33, v19
	v_add_u32_e32 v33, v130, v19
	ds_write_b32 v33, v20
	v_mov_b32_e32 v20, 0x1aa90
	v_mad_u32_u24 v20, v131, s33, v20
	v_add_u32_e32 v33, v130, v20
	ds_write_b32 v33, v21
	v_mov_b32_e32 v21, 0x1aea0
	v_mad_u32_u24 v21, v131, s33, v21
	v_add_u32_e32 v33, v130, v21
	ds_write_b32 v33, v22
	v_mov_b32_e32 v22, 0x1b2b0
	v_mad_u32_u24 v22, v131, s33, v22
	v_add_u32_e32 v33, v130, v22
	ds_write_b32 v33, v23
	v_mov_b32_e32 v23, 0x1c700
	v_mad_u32_u24 v23, v131, s33, v23
	v_add_u32_e32 v33, v130, v23
	ds_write_b32 v33, v24
	v_mov_b32_e32 v24, 0x1cb10
	v_mad_u32_u24 v24, v131, s33, v24
	v_add_u32_e32 v33, v130, v24
	ds_write_b32 v33, v25
	v_mov_b32_e32 v25, 0x1cf20
	v_mad_u32_u24 v25, v131, s33, v25
	v_add_u32_e32 v33, v130, v25
	ds_write_b32 v33, v26
	v_mov_b32_e32 v26, 0x1d330
	v_mad_u32_u24 v26, v131, s33, v26
	v_add_u32_e32 v33, v130, v26
	ds_write_b32 v33, v27
	v_mov_b32_e32 v27, 0x1e780
	v_mad_u32_u24 v27, v131, s33, v27
	v_add_u32_e32 v33, v130, v27
	ds_write_b32 v33, v28
	v_mov_b32_e32 v28, 0x1eb90
	v_mad_u32_u24 v28, v131, s33, v28
	v_add_u32_e32 v33, v130, v28
	ds_write_b32 v33, v29
	v_mov_b32_e32 v29, 0x1efa0
	v_mad_u32_u24 v29, v131, s33, v29
	v_add_u32_e32 v33, v130, v29
	ds_write_b32 v33, v30
	v_mov_b32_e32 v30, 0x1f3b0
	v_mad_u32_u24 v30, v131, s33, v30
	v_add_u32_e32 v33, v130, v30
	ds_write_b32 v33, v31
	v_add_u32_e32 v31, v133, v32
	ds_write_b32 v31, v0
	v_add_u32_e32 v0, v133, v16
	ds_write_b32 v0, v1
	v_add_u32_e32 v0, v133, v17
	ds_write_b32 v0, v2
	v_add_u32_e32 v0, v133, v18
	ds_write_b32 v0, v3
	v_add_u32_e32 v0, v133, v19
	ds_write_b32 v0, v4
	v_add_u32_e32 v0, v133, v20
	ds_write_b32 v0, v5
	v_add_u32_e32 v0, v133, v21
	ds_write_b32 v0, v6
	v_add_u32_e32 v0, v133, v22
	ds_write_b32 v0, v7
	v_add_u32_e32 v0, v133, v23
	ds_write_b32 v0, v8
	v_add_u32_e32 v0, v133, v24
	ds_write_b32 v0, v9
	v_add_u32_e32 v0, v133, v25
	ds_write_b32 v0, v10
	v_add_u32_e32 v0, v133, v26
	ds_write_b32 v0, v11
	v_add_u32_e32 v0, v133, v27
	ds_write_b32 v0, v12
	v_add_u32_e32 v0, v133, v28
	ds_write_b32 v0, v13
	v_add_u32_e32 v0, v133, v29
	ds_write_b32 v0, v14
	v_add_u32_e32 v0, v133, v30
	ds_write_b32 v0, v15
	s_branch .LBB0_93

.LBB0_166:
	s_add_i32 s8, s8, s11
	s_add_i32 s9, s9, s10
	s_movk_i32 s20, 0x4000
	s_cmpk_gt_u32 s8, 0x4ff
	s_movk_i32 s19, 0x8000
	s_barrier
	s_cbranch_scc1 .LBB0_247

.LBB0_181:
	s_waitcnt vmcnt(0) lgkmcnt(0)
	s_barrier
	s_ashr_i32 s47, s46, 31
	v_lshl_add_u64 v[134:135], s[46:47], 2, v[180:181]
	v_cndmask_b32_e64 v132, 0, 1, s[42:43]
	s_nop 1
	v_cmp_ne_u32_e64 s[38:39], 1, v132
	v_lshlrev_b32_e32 v132, 2, v178
	v_mov_b32_e32 v133, v177
	v_readlane_b32 s48, v253, 12
	v_readlane_b32 s49, v253, 13
	v_readlane_b32 s50, v253, 14
	v_readlane_b32 s51, v253, 15
	v_mov_b32_e32 v131, 0
	v_add_u32_e32 v160, s13, v179
	v_ashrrev_i32_e32 v161, 31, v160
	v_lshlrev_b64 v[136:137], 12, v[160:161]
	v_lshl_add_u64 v[136:137], v[134:135], 0, v[136:137]
	v_add_u32_e32 v164, s13, v243
	v_ashrrev_i32_e32 v165, 31, v164
	v_lshlrev_b64 v[138:139], 12, v[164:165]
	v_lshl_add_u64 v[138:139], v[134:135], 0, v[138:139]
	v_add_u32_e32 v168, s13, v244
	v_ashrrev_i32_e32 v169, 31, v168
	v_lshlrev_b64 v[140:141], 12, v[168:169]
	v_lshl_add_u64 v[140:141], v[134:135], 0, v[140:141]
	v_add_u32_e32 v172, s13, v245
	v_ashrrev_i32_e32 v173, 31, v172
	v_lshlrev_b64 v[142:143], 12, v[172:173]
	v_lshl_add_u64 v[142:143], v[134:135], 0, v[142:143]
	s_and_b64 vcc, exec, s[38:39]
	s_cbranch_vccnz .Lroa0_nofi
	v_add_u32_e32 v130, 0xffffc000, v160
	v_lshlrev_b64 v[144:145], 10, v[160:161]
	v_cmp_gt_i32_e32 vcc, s2, v160
	v_lshlrev_b64 v[146:147], 12, v[130:131]
	v_lshl_add_u64 v[144:145], v[144:145], 2, s[48:49]
	v_lshl_add_u64 v[146:147], s[50:51], 0, v[146:147]
	v_cndmask_b32_e32 v147, v147, v145, vcc
	v_cndmask_b32_e32 v146, v146, v144, vcc
	v_lshl_add_u64 v[146:147], s[46:47], 2, v[146:147]
	v_lshl_add_u64 v[146:147], v[146:147], 0, v[132:133]
	v_add_u32_e32 v130, 0xffffc000, v164
	v_lshlrev_b64 v[148:149], 10, v[164:165]
	v_cmp_gt_i32_e32 vcc, s2, v164
	v_lshlrev_b64 v[150:151], 12, v[130:131]
	v_lshl_add_u64 v[148:149], v[148:149], 2, s[48:49]
	v_lshl_add_u64 v[150:151], s[50:51], 0, v[150:151]
	v_cndmask_b32_e32 v151, v151, v149, vcc
	v_cndmask_b32_e32 v150, v150, v148, vcc
	v_lshl_add_u64 v[150:151], s[46:47], 2, v[150:151]
	v_lshl_add_u64 v[150:151], v[150:151], 0, v[132:133]
	v_add_u32_e32 v130, 0xffffc000, v168
	v_lshlrev_b64 v[152:153], 10, v[168:169]
	v_cmp_gt_i32_e32 vcc, s2, v168
	v_lshlrev_b64 v[154:155], 12, v[130:131]
	v_lshl_add_u64 v[152:153], v[152:153], 2, s[48:49]
	v_lshl_add_u64 v[154:155], s[50:51], 0, v[154:155]
	v_cndmask_b32_e32 v155, v155, v153, vcc
	v_cndmask_b32_e32 v154, v154, v152, vcc
	v_lshl_add_u64 v[154:155], s[46:47], 2, v[154:155]
	v_lshl_add_u64 v[154:155], v[154:155], 0, v[132:133]
	v_add_u32_e32 v130, 0xffffc000, v172
	v_lshlrev_b64 v[156:157], 10, v[172:173]
	v_cmp_gt_i32_e32 vcc, s2, v172
	v_lshlrev_b64 v[158:159], 12, v[130:131]
	v_lshl_add_u64 v[156:157], v[156:157], 2, s[48:49]
	v_lshl_add_u64 v[158:159], s[50:51], 0, v[158:159]
	v_cndmask_b32_e32 v159, v159, v157, vcc
	v_cndmask_b32_e32 v158, v158, v156, vcc
	v_lshl_add_u64 v[158:159], s[46:47], 2, v[158:159]
	v_lshl_add_u64 v[158:159], v[158:159], 0, v[132:133]
	s_branch .Lroa0_ld
.Lroa0_nofi:
	v_mov_b64_e32 v[146:147], v[136:137]
	v_mov_b64_e32 v[150:151], v[138:139]
	v_mov_b64_e32 v[154:155], v[140:141]
	v_mov_b64_e32 v[158:159], v[142:143]
.Lroa0_ld:
	global_load_dwordx4 v[144:147], v[146:147], off
	s_nop 0
	global_load_dwordx4 v[148:151], v[150:151], off
	s_nop 0
	global_load_dwordx4 v[152:155], v[154:155], off
	s_nop 0
	global_load_dwordx4 v[156:159], v[158:159], off
	s_nop 0
	ds_read_b128 v[160:163], v200
	ds_read_b128 v[164:167], v201
	ds_read_b128 v[168:171], v242
	ds_read_b128 v[172:175], v238
	s_waitcnt vmcnt(3) lgkmcnt(3)
	v_pk_add_f32 v[160:161], v[160:161], v[144:145]
	v_pk_add_f32 v[162:163], v[162:163], v[146:147]
	global_store_dwordx4 v[136:137], v[160:163], off
	s_waitcnt vmcnt(3) lgkmcnt(2)
	v_pk_add_f32 v[164:165], v[164:165], v[148:149]
	v_pk_add_f32 v[166:167], v[166:167], v[150:151]
	global_store_dwordx4 v[138:139], v[164:167], off
	s_waitcnt vmcnt(3) lgkmcnt(1)
	v_pk_add_f32 v[168:169], v[168:169], v[152:153]
	v_pk_add_f32 v[170:171], v[170:171], v[154:155]
	global_store_dwordx4 v[140:141], v[168:171], off
	s_waitcnt vmcnt(3) lgkmcnt(0)
	v_pk_add_f32 v[172:173], v[172:173], v[156:157]
	v_pk_add_f32 v[174:175], v[174:175], v[158:159]
	global_store_dwordx4 v[142:143], v[172:175], off
	v_add_u32_e32 v160, s13, v246
	v_ashrrev_i32_e32 v161, 31, v160
	v_lshlrev_b64 v[136:137], 12, v[160:161]
	v_lshl_add_u64 v[136:137], v[134:135], 0, v[136:137]
	v_add_u32_e32 v164, s13, v247
	v_ashrrev_i32_e32 v165, 31, v164
	v_lshlrev_b64 v[138:139], 12, v[164:165]
	v_lshl_add_u64 v[138:139], v[134:135], 0, v[138:139]
	v_add_u32_e32 v168, s13, v248
	v_ashrrev_i32_e32 v169, 31, v168
	v_lshlrev_b64 v[140:141], 12, v[168:169]
	v_lshl_add_u64 v[140:141], v[134:135], 0, v[140:141]
	v_add_u32_e32 v172, s13, v249
	v_ashrrev_i32_e32 v173, 31, v172
	v_lshlrev_b64 v[142:143], 12, v[172:173]
	v_lshl_add_u64 v[142:143], v[134:135], 0, v[142:143]
	s_and_b64 vcc, exec, s[38:39]
	s_cbranch_vccnz .Lroa1_nofi
	v_add_u32_e32 v130, 0xffffc000, v160
	v_lshlrev_b64 v[144:145], 10, v[160:161]
	v_cmp_gt_i32_e32 vcc, s2, v160
	v_lshlrev_b64 v[146:147], 12, v[130:131]
	v_lshl_add_u64 v[144:145], v[144:145], 2, s[48:49]
	v_lshl_add_u64 v[146:147], s[50:51], 0, v[146:147]
	v_cndmask_b32_e32 v147, v147, v145, vcc
	v_cndmask_b32_e32 v146, v146, v144, vcc
	v_lshl_add_u64 v[146:147], s[46:47], 2, v[146:147]
	v_lshl_add_u64 v[146:147], v[146:147], 0, v[132:133]
	v_add_u32_e32 v130, 0xffffc000, v164
	v_lshlrev_b64 v[148:149], 10, v[164:165]
	v_cmp_gt_i32_e32 vcc, s2, v164
	v_lshlrev_b64 v[150:151], 12, v[130:131]
	v_lshl_add_u64 v[148:149], v[148:149], 2, s[48:49]
	v_lshl_add_u64 v[150:151], s[50:51], 0, v[150:151]
	v_cndmask_b32_e32 v151, v151, v149, vcc
	v_cndmask_b32_e32 v150, v150, v148, vcc
	v_lshl_add_u64 v[150:151], s[46:47], 2, v[150:151]
	v_lshl_add_u64 v[150:151], v[150:151], 0, v[132:133]
	v_add_u32_e32 v130, 0xffffc000, v168
	v_lshlrev_b64 v[152:153], 10, v[168:169]
	v_cmp_gt_i32_e32 vcc, s2, v168
	v_lshlrev_b64 v[154:155], 12, v[130:131]
	v_lshl_add_u64 v[152:153], v[152:153], 2, s[48:49]
	v_lshl_add_u64 v[154:155], s[50:51], 0, v[154:155]
	v_cndmask_b32_e32 v155, v155, v153, vcc
	v_cndmask_b32_e32 v154, v154, v152, vcc
	v_lshl_add_u64 v[154:155], s[46:47], 2, v[154:155]
	v_lshl_add_u64 v[154:155], v[154:155], 0, v[132:133]
	v_add_u32_e32 v130, 0xffffc000, v172
	v_lshlrev_b64 v[156:157], 10, v[172:173]
	v_cmp_gt_i32_e32 vcc, s2, v172
	v_lshlrev_b64 v[158:159], 12, v[130:131]
	v_lshl_add_u64 v[156:157], v[156:157], 2, s[48:49]
	v_lshl_add_u64 v[158:159], s[50:51], 0, v[158:159]
	v_cndmask_b32_e32 v159, v159, v157, vcc
	v_cndmask_b32_e32 v158, v158, v156, vcc
	v_lshl_add_u64 v[158:159], s[46:47], 2, v[158:159]
	v_lshl_add_u64 v[158:159], v[158:159], 0, v[132:133]
	s_branch .Lroa1_ld

.Lroa1_ld:
	global_load_dwordx4 v[144:147], v[146:147], off
	s_nop 0
	global_load_dwordx4 v[148:151], v[150:151], off
	s_nop 0
	global_load_dwordx4 v[152:155], v[154:155], off
	s_nop 0
	global_load_dwordx4 v[156:159], v[158:159], off
	s_nop 0
	ds_read_b128 v[160:163], v205
	ds_read_b128 v[164:167], v209
	ds_read_b128 v[168:171], v213
	ds_read_b128 v[172:175], v217
	s_waitcnt vmcnt(3) lgkmcnt(3)
	v_pk_add_f32 v[160:161], v[160:161], v[144:145]
	v_pk_add_f32 v[162:163], v[162:163], v[146:147]
	global_store_dwordx4 v[136:137], v[160:163], off
	s_waitcnt vmcnt(3) lgkmcnt(2)
	v_pk_add_f32 v[164:165], v[164:165], v[148:149]
	v_pk_add_f32 v[166:167], v[166:167], v[150:151]
	global_store_dwordx4 v[138:139], v[164:167], off
	s_waitcnt vmcnt(3) lgkmcnt(1)
	v_pk_add_f32 v[168:169], v[168:169], v[152:153]
	v_pk_add_f32 v[170:171], v[170:171], v[154:155]
	global_store_dwordx4 v[140:141], v[168:171], off
	s_waitcnt vmcnt(3) lgkmcnt(0)
	v_pk_add_f32 v[172:173], v[172:173], v[156:157]
	v_pk_add_f32 v[174:175], v[174:175], v[158:159]
	global_store_dwordx4 v[142:143], v[172:175], off
	v_add_u32_e32 v160, s13, v250
	v_ashrrev_i32_e32 v161, 31, v160
	v_lshlrev_b64 v[136:137], 12, v[160:161]
	v_lshl_add_u64 v[136:137], v[134:135], 0, v[136:137]
	v_add_u32_e32 v164, s13, v251
	v_ashrrev_i32_e32 v165, 31, v164
	v_lshlrev_b64 v[138:139], 12, v[164:165]
	v_lshl_add_u64 v[138:139], v[134:135], 0, v[138:139]
	v_add_u32_e32 v168, s13, v241
	v_ashrrev_i32_e32 v169, 31, v168
	v_lshlrev_b64 v[140:141], 12, v[168:169]
	v_lshl_add_u64 v[140:141], v[134:135], 0, v[140:141]
	v_add_u32_e32 v172, s13, v191
	v_ashrrev_i32_e32 v173, 31, v172
	v_lshlrev_b64 v[142:143], 12, v[172:173]
	v_lshl_add_u64 v[142:143], v[134:135], 0, v[142:143]
	s_and_b64 vcc, exec, s[38:39]
	s_cbranch_vccnz .Lroa2_nofi
	v_add_u32_e32 v130, 0xffffc000, v160
	v_lshlrev_b64 v[144:145], 10, v[160:161]
	v_cmp_gt_i32_e32 vcc, s2, v160
	v_lshlrev_b64 v[146:147], 12, v[130:131]
	v_lshl_add_u64 v[144:145], v[144:145], 2, s[48:49]
	v_lshl_add_u64 v[146:147], s[50:51], 0, v[146:147]
	v_cndmask_b32_e32 v147, v147, v145, vcc
	v_cndmask_b32_e32 v146, v146, v144, vcc
	v_lshl_add_u64 v[146:147], s[46:47], 2, v[146:147]
	v_lshl_add_u64 v[146:147], v[146:147], 0, v[132:133]
	v_add_u32_e32 v130, 0xffffc000, v164
	v_lshlrev_b64 v[148:149], 10, v[164:165]
	v_cmp_gt_i32_e32 vcc, s2, v164
	v_lshlrev_b64 v[150:151], 12, v[130:131]
	v_lshl_add_u64 v[148:149], v[148:149], 2, s[48:49]
	v_lshl_add_u64 v[150:151], s[50:51], 0, v[150:151]
	v_cndmask_b32_e32 v151, v151, v149, vcc
	v_cndmask_b32_e32 v150, v150, v148, vcc
	v_lshl_add_u64 v[150:151], s[46:47], 2, v[150:151]
	v_lshl_add_u64 v[150:151], v[150:151], 0, v[132:133]
	v_add_u32_e32 v130, 0xffffc000, v168
	v_lshlrev_b64 v[152:153], 10, v[168:169]
	v_cmp_gt_i32_e32 vcc, s2, v168
	v_lshlrev_b64 v[154:155], 12, v[130:131]
	v_lshl_add_u64 v[152:153], v[152:153], 2, s[48:49]
	v_lshl_add_u64 v[154:155], s[50:51], 0, v[154:155]
	v_cndmask_b32_e32 v155, v155, v153, vcc
	v_cndmask_b32_e32 v154, v154, v152, vcc
	v_lshl_add_u64 v[154:155], s[46:47], 2, v[154:155]
	v_lshl_add_u64 v[154:155], v[154:155], 0, v[132:133]
	v_add_u32_e32 v130, 0xffffc000, v172
	v_lshlrev_b64 v[156:157], 10, v[172:173]
	v_cmp_gt_i32_e32 vcc, s2, v172
	v_lshlrev_b64 v[158:159], 12, v[130:131]
	v_lshl_add_u64 v[156:157], v[156:157], 2, s[48:49]
	v_lshl_add_u64 v[158:159], s[50:51], 0, v[158:159]
	v_cndmask_b32_e32 v159, v159, v157, vcc
	v_cndmask_b32_e32 v158, v158, v156, vcc
	v_lshl_add_u64 v[158:159], s[46:47], 2, v[158:159]
	v_lshl_add_u64 v[158:159], v[158:159], 0, v[132:133]
	s_branch .Lroa2_ld

.Lroa2_ld:
	global_load_dwordx4 v[144:147], v[146:147], off
	s_nop 0
	global_load_dwordx4 v[148:151], v[150:151], off
	s_nop 0
	global_load_dwordx4 v[152:155], v[154:155], off
	s_nop 0
	global_load_dwordx4 v[156:159], v[158:159], off
	s_nop 0
	ds_read_b128 v[160:163], v221
	ds_read_b128 v[164:167], v225
	ds_read_b128 v[168:171], v229
	ds_read_b128 v[172:175], v233
	s_waitcnt vmcnt(3) lgkmcnt(3)
	v_pk_add_f32 v[160:161], v[160:161], v[144:145]
	v_pk_add_f32 v[162:163], v[162:163], v[146:147]
	global_store_dwordx4 v[136:137], v[160:163], off
	s_waitcnt vmcnt(3) lgkmcnt(2)
	v_pk_add_f32 v[164:165], v[164:165], v[148:149]
	v_pk_add_f32 v[166:167], v[166:167], v[150:151]
	global_store_dwordx4 v[138:139], v[164:167], off
	s_waitcnt vmcnt(3) lgkmcnt(1)
	v_pk_add_f32 v[168:169], v[168:169], v[152:153]
	v_pk_add_f32 v[170:171], v[170:171], v[154:155]
	global_store_dwordx4 v[140:141], v[168:171], off
	s_waitcnt vmcnt(3) lgkmcnt(0)
	v_pk_add_f32 v[172:173], v[172:173], v[156:157]
	v_pk_add_f32 v[174:175], v[174:175], v[158:159]
	global_store_dwordx4 v[142:143], v[172:175], off
	v_add_u32_e32 v160, s13, v192
	v_ashrrev_i32_e32 v161, 31, v160
	v_lshlrev_b64 v[136:137], 12, v[160:161]
	v_lshl_add_u64 v[136:137], v[134:135], 0, v[136:137]
	v_add_u32_e32 v164, s13, v197
	v_ashrrev_i32_e32 v165, 31, v164
	v_lshlrev_b64 v[138:139], 12, v[164:165]
	v_lshl_add_u64 v[138:139], v[134:135], 0, v[138:139]
	v_add_u32_e32 v168, s13, v198
	v_ashrrev_i32_e32 v169, 31, v168
	v_lshlrev_b64 v[140:141], 12, v[168:169]
	v_lshl_add_u64 v[140:141], v[134:135], 0, v[140:141]
	v_add_u32_e32 v172, s13, v199
	v_ashrrev_i32_e32 v173, 31, v172
	v_lshlrev_b64 v[142:143], 12, v[172:173]
	v_lshl_add_u64 v[142:143], v[134:135], 0, v[142:143]
	s_and_b64 vcc, exec, s[38:39]
	s_cbranch_vccnz .Lroa3_nofi
	v_add_u32_e32 v130, 0xffffc000, v160
	v_lshlrev_b64 v[144:145], 10, v[160:161]
	v_cmp_gt_i32_e32 vcc, s2, v160
	v_lshlrev_b64 v[146:147], 12, v[130:131]
	v_lshl_add_u64 v[144:145], v[144:145], 2, s[48:49]
	v_lshl_add_u64 v[146:147], s[50:51], 0, v[146:147]
	v_cndmask_b32_e32 v147, v147, v145, vcc
	v_cndmask_b32_e32 v146, v146, v144, vcc
	v_lshl_add_u64 v[146:147], s[46:47], 2, v[146:147]
	v_lshl_add_u64 v[146:147], v[146:147], 0, v[132:133]
	v_add_u32_e32 v130, 0xffffc000, v164
	v_lshlrev_b64 v[148:149], 10, v[164:165]
	v_cmp_gt_i32_e32 vcc, s2, v164
	v_lshlrev_b64 v[150:151], 12, v[130:131]
	v_lshl_add_u64 v[148:149], v[148:149], 2, s[48:49]
	v_lshl_add_u64 v[150:151], s[50:51], 0, v[150:151]
	v_cndmask_b32_e32 v151, v151, v149, vcc
	v_cndmask_b32_e32 v150, v150, v148, vcc
	v_lshl_add_u64 v[150:151], s[46:47], 2, v[150:151]
	v_lshl_add_u64 v[150:151], v[150:151], 0, v[132:133]
	v_add_u32_e32 v130, 0xffffc000, v168
	v_lshlrev_b64 v[152:153], 10, v[168:169]
	v_cmp_gt_i32_e32 vcc, s2, v168
	v_lshlrev_b64 v[154:155], 12, v[130:131]
	v_lshl_add_u64 v[152:153], v[152:153], 2, s[48:49]
	v_lshl_add_u64 v[154:155], s[50:51], 0, v[154:155]
	v_cndmask_b32_e32 v155, v155, v153, vcc
	v_cndmask_b32_e32 v154, v154, v152, vcc
	v_lshl_add_u64 v[154:155], s[46:47], 2, v[154:155]
	v_lshl_add_u64 v[154:155], v[154:155], 0, v[132:133]
	v_add_u32_e32 v130, 0xffffc000, v172
	v_lshlrev_b64 v[156:157], 10, v[172:173]
	v_cmp_gt_i32_e32 vcc, s2, v172
	v_lshlrev_b64 v[158:159], 12, v[130:131]
	v_lshl_add_u64 v[156:157], v[156:157], 2, s[48:49]
	v_lshl_add_u64 v[158:159], s[50:51], 0, v[158:159]
	v_cndmask_b32_e32 v159, v159, v157, vcc
	v_cndmask_b32_e32 v158, v158, v156, vcc
	v_lshl_add_u64 v[158:159], s[46:47], 2, v[158:159]
	v_lshl_add_u64 v[158:159], v[158:159], 0, v[132:133]
	s_branch .Lroa3_ld

.Lroa3_ld:
	global_load_dwordx4 v[144:147], v[146:147], off
	s_nop 0
	global_load_dwordx4 v[148:151], v[150:151], off
	s_nop 0
	global_load_dwordx4 v[152:155], v[154:155], off
	s_nop 0
	global_load_dwordx4 v[156:159], v[158:159], off
	s_nop 0
	ds_read_b128 v[160:163], v206
	ds_read_b128 v[164:167], v207
	ds_read_b128 v[168:171], v208
	ds_read_b128 v[172:175], v210
	s_waitcnt vmcnt(3) lgkmcnt(3)
	v_pk_add_f32 v[160:161], v[160:161], v[144:145]
	v_pk_add_f32 v[162:163], v[162:163], v[146:147]
	global_store_dwordx4 v[136:137], v[160:163], off
	s_waitcnt vmcnt(3) lgkmcnt(2)
	v_pk_add_f32 v[164:165], v[164:165], v[148:149]
	v_pk_add_f32 v[166:167], v[166:167], v[150:151]
	global_store_dwordx4 v[138:139], v[164:167], off
	s_waitcnt vmcnt(3) lgkmcnt(1)
	v_pk_add_f32 v[168:169], v[168:169], v[152:153]
	v_pk_add_f32 v[170:171], v[170:171], v[154:155]
	global_store_dwordx4 v[140:141], v[168:171], off
	s_waitcnt vmcnt(3) lgkmcnt(0)
	v_pk_add_f32 v[172:173], v[172:173], v[156:157]
	v_pk_add_f32 v[174:175], v[174:175], v[158:159]
	global_store_dwordx4 v[142:143], v[172:175], off
	s_barrier
	s_nop 0
	v_mov_b32_e32 v128, v190
	s_nop 0
	v_readfirstlane_b32 s4, v128
	s_and_b32 s5, s4, 0xffffff00
	s_cmpk_lg_i32 s5, 0x100
	s_cbranch_scc1 .LBB0_215
	s_and_b32 s4, s4, 0xc0
	v_lshrrev_b32_e32 v129, 3, v128
	v_and_or_b32 v128, v128, 31, s4
	v_and_b32_e32 v129, 4, v129
	v_lshlrev_b32_e32 v128, 2, v128
	v_mad_u32_u24 v130, v129, s33, v128
	ds_write2_b32 v130, v112, v96 offset1:32
	v_add_u32_e32 v96, 0x400, v130
	ds_write2_b32 v96, v113, v97 offset0:4 offset1:36
	v_add_u32_e32 v96, 0x800, v130
	ds_write2_b32 v96, v114, v98 offset0:8 offset1:40
	v_add_u32_e32 v96, 0xc00, v130
	ds_write2_b32 v96, v115, v99 offset0:12 offset1:44
	v_add_u32_e32 v96, 0x2000, v130
	ds_write2_b32 v96, v116, v100 offset0:32 offset1:64
	v_add_u32_e32 v96, 0x2400, v130
	ds_write2_b32 v96, v117, v101 offset0:36 offset1:68
	v_add_u32_e32 v96, 0x2800, v130
	ds_write2_b32 v96, v118, v102 offset0:40 offset1:72
	v_add_u32_e32 v96, 0x2c00, v130
	ds_write2_b32 v96, v119, v103 offset0:44 offset1:76
	v_add_u32_e32 v96, 0x4000, v130
	ds_write2_b32 v96, v120, v104 offset0:64 offset1:96
	v_add_u32_e32 v96, 0x4400, v130
	ds_write2_b32 v96, v121, v105 offset0:68 offset1:100
	v_add_u32_e32 v96, 0x4800, v130
	ds_write2_b32 v96, v122, v106 offset0:72 offset1:104
	v_add_u32_e32 v96, 0x4c00, v130
	ds_write2_b32 v96, v123, v107 offset0:76 offset1:108
	v_add_u32_e32 v96, 0x6000, v130
	ds_write2_b32 v96, v124, v108 offset0:96 offset1:128
	v_add_u32_e32 v96, 0x6400, v130
	ds_write2_b32 v96, v125, v109 offset0:100 offset1:132
	v_add_u32_e32 v96, 0x6800, v130
	ds_write2_b32 v96, v126, v110 offset0:104 offset1:136
	v_add_u32_e32 v96, 0x6c00, v130
	ds_write2_b32 v96, v127, v111 offset0:108 offset1:140
	v_add_u32_e32 v96, 0x8000, v130
	ds_write2_b32 v96, v80, v64 offset0:128 offset1:160
	v_add_u32_e32 v64, 0x8400, v130
	ds_write2_b32 v64, v81, v65 offset0:132 offset1:164
	v_add_u32_e32 v64, 0x8800, v130
	ds_write2_b32 v64, v82, v66 offset0:136 offset1:168
	v_add_u32_e32 v64, 0x8c00, v130
	ds_write2_b32 v64, v83, v67 offset0:140 offset1:172
	v_add_u32_e32 v64, 0xa000, v130
	ds_write2_b32 v64, v84, v68 offset0:160 offset1:192
	v_add_u32_e32 v64, 0xa400, v130
	ds_write2_b32 v64, v85, v69 offset0:164 offset1:196
	v_add_u32_e32 v64, 0xa800, v130
	ds_write2_b32 v64, v86, v70 offset0:168 offset1:200
	v_add_u32_e32 v64, 0xac00, v130
	ds_write2_b32 v64, v87, v71 offset0:172 offset1:204
	v_add_u32_e32 v64, 0xc000, v130
	ds_write2_b32 v64, v88, v72 offset0:192 offset1:224
	v_add_u32_e32 v64, 0xc400, v130
	ds_write2_b32 v64, v89, v73 offset0:196 offset1:228
	v_add_u32_e32 v64, 0xc800, v130
	ds_write2_b32 v64, v90, v74 offset0:200 offset1:232
	v_add_u32_e32 v64, 0xcc00, v130
	ds_write2_b32 v64, v91, v75 offset0:204 offset1:236
	v_add_u32_e32 v64, 0xe200, v130
	ds_write2_b32 v64, v92, v76 offset0:96 offset1:128
	v_add_u32_e32 v64, 0xe600, v130
	ds_write2_b32 v64, v93, v77 offset0:100 offset1:132
	v_add_u32_e32 v64, 0xea00, v130
	ds_write2_b32 v64, v94, v78 offset0:104 offset1:136
	v_add_u32_e32 v64, 0xee00, v130
	ds_write2_b32 v64, v95, v79 offset0:108 offset1:140
	v_mov_b32_e32 v64, 0x10400
	v_mad_u32_u24 v64, v129, s33, v64
	v_add_u32_e32 v65, v128, v64
	ds_write_b32 v65, v48
	v_mov_b32_e32 v48, 0x10810
	v_mad_u32_u24 v48, v129, s33, v48
	v_add_u32_e32 v65, v128, v48
	ds_write_b32 v65, v49
	v_mov_b32_e32 v49, 0x10c20
	v_mad_u32_u24 v49, v129, s33, v49
	v_add_u32_e32 v65, v128, v49
	ds_write_b32 v65, v50
	v_mov_b32_e32 v50, 0x11030
	v_mad_u32_u24 v50, v129, s33, v50
	v_add_u32_e32 v65, v128, v50
	ds_write_b32 v65, v51
	v_mov_b32_e32 v51, 0x12480
	v_mad_u32_u24 v51, v129, s33, v51
	v_add_u32_e32 v65, v128, v51
	ds_write_b32 v65, v52
	v_mov_b32_e32 v52, 0x12890
	v_mad_u32_u24 v52, v129, s33, v52
	v_add_u32_e32 v65, v128, v52
	ds_write_b32 v65, v53
	v_mov_b32_e32 v53, 0x12ca0
	v_mad_u32_u24 v53, v129, s33, v53
	v_add_u32_e32 v65, v128, v53
	ds_write_b32 v65, v54
	v_mov_b32_e32 v54, 0x130b0
	v_mad_u32_u24 v54, v129, s33, v54
	v_add_u32_e32 v65, v128, v54
	ds_write_b32 v65, v55
	v_mov_b32_e32 v55, 0x14500
	v_mad_u32_u24 v55, v129, s33, v55
	v_add_u32_e32 v65, v128, v55
	ds_write_b32 v65, v56
	v_mov_b32_e32 v56, 0x14910
	v_mad_u32_u24 v56, v129, s33, v56
	v_add_u32_e32 v65, v128, v56
	ds_write_b32 v65, v57
	v_mov_b32_e32 v57, 0x14d20
	v_mad_u32_u24 v57, v129, s33, v57
	v_add_u32_e32 v65, v128, v57
	ds_write_b32 v65, v58
	v_mov_b32_e32 v58, 0x15130
	v_mad_u32_u24 v58, v129, s33, v58
	v_add_u32_e32 v65, v128, v58
	ds_write_b32 v65, v59
	v_mov_b32_e32 v59, 0x16580
	v_mad_u32_u24 v59, v129, s33, v59
	v_add_u32_e32 v65, v128, v59
	ds_write_b32 v65, v60
	v_mov_b32_e32 v60, 0x16990
	v_mad_u32_u24 v60, v129, s33, v60
	v_add_u32_e32 v65, v128, v60
	ds_write_b32 v65, v61
	v_mov_b32_e32 v61, 0x16da0
	v_mad_u32_u24 v61, v129, s33, v61
	v_add_u32_e32 v65, v128, v61
	ds_write_b32 v65, v62
	v_mov_b32_e32 v62, 0x171b0
	v_mad_u32_u24 v62, v129, s33, v62
	v_or_b32_e32 v131, 0x80, v128
	v_add_u32_e32 v65, v128, v62
	ds_write_b32 v65, v63
	v_add_u32_e32 v63, v131, v64
	ds_write_b32 v63, v32
	v_add_u32_e32 v32, v131, v48
	ds_write_b32 v32, v33
	v_add_u32_e32 v32, v131, v49
	ds_write_b32 v32, v34
	v_add_u32_e32 v32, v131, v50
	ds_write_b32 v32, v35
	v_add_u32_e32 v32, v131, v51
	ds_write_b32 v32, v36
	v_add_u32_e32 v32, v131, v52
	ds_write_b32 v32, v37
	v_add_u32_e32 v32, v131, v53
	ds_write_b32 v32, v38
	v_add_u32_e32 v32, v131, v54
	ds_write_b32 v32, v39
	v_add_u32_e32 v32, v131, v55
	ds_write_b32 v32, v40
	v_add_u32_e32 v32, v131, v56
	ds_write_b32 v32, v41
	v_add_u32_e32 v32, v131, v57
	ds_write_b32 v32, v42
	v_add_u32_e32 v32, v131, v58
	ds_write_b32 v32, v43
	v_add_u32_e32 v32, v131, v59
	ds_write_b32 v32, v44
	v_add_u32_e32 v32, v131, v60
	ds_write_b32 v32, v45
	v_add_u32_e32 v32, v131, v61
	ds_write_b32 v32, v46
	v_add_u32_e32 v32, v131, v62
	ds_write_b32 v32, v47
	v_mov_b32_e32 v32, 0x18600
	v_mad_u32_u24 v32, v129, s33, v32
	v_add_u32_e32 v33, v128, v32
	ds_write_b32 v33, v16
	v_mov_b32_e32 v16, 0x18a10
	v_mad_u32_u24 v16, v129, s33, v16
	v_add_u32_e32 v33, v128, v16
	ds_write_b32 v33, v17
	v_mov_b32_e32 v17, 0x18e20
	v_mad_u32_u24 v17, v129, s33, v17
	v_add_u32_e32 v33, v128, v17
	ds_write_b32 v33, v18
	v_mov_b32_e32 v18, 0x19230
	v_mad_u32_u24 v18, v129, s33, v18
	v_add_u32_e32 v33, v128, v18
	ds_write_b32 v33, v19
	v_mov_b32_e32 v19, 0x1a680
	v_mad_u32_u24 v19, v129, s33, v19
	v_add_u32_e32 v33, v128, v19
	ds_write_b32 v33, v20
	v_mov_b32_e32 v20, 0x1aa90
	v_mad_u32_u24 v20, v129, s33, v20
	v_add_u32_e32 v33, v128, v20
	ds_write_b32 v33, v21
	v_mov_b32_e32 v21, 0x1aea0
	v_mad_u32_u24 v21, v129, s33, v21
	v_add_u32_e32 v33, v128, v21
	ds_write_b32 v33, v22
	v_mov_b32_e32 v22, 0x1b2b0
	v_mad_u32_u24 v22, v129, s33, v22
	v_add_u32_e32 v33, v128, v22
	ds_write_b32 v33, v23
	v_mov_b32_e32 v23, 0x1c700
	v_mad_u32_u24 v23, v129, s33, v23
	v_add_u32_e32 v33, v128, v23
	ds_write_b32 v33, v24
	v_mov_b32_e32 v24, 0x1cb10
	v_mad_u32_u24 v24, v129, s33, v24
	v_add_u32_e32 v33, v128, v24
	ds_write_b32 v33, v25
	v_mov_b32_e32 v25, 0x1cf20
	v_mad_u32_u24 v25, v129, s33, v25
	v_add_u32_e32 v33, v128, v25
	ds_write_b32 v33, v26
	v_mov_b32_e32 v26, 0x1d330
	v_mad_u32_u24 v26, v129, s33, v26
	v_add_u32_e32 v33, v128, v26
	ds_write_b32 v33, v27
	v_mov_b32_e32 v27, 0x1e780
	v_mad_u32_u24 v27, v129, s33, v27
	v_add_u32_e32 v33, v128, v27
	ds_write_b32 v33, v28
	v_mov_b32_e32 v28, 0x1eb90
	v_mad_u32_u24 v28, v129, s33, v28
	v_add_u32_e32 v33, v128, v28
	ds_write_b32 v33, v29
	v_mov_b32_e32 v29, 0x1efa0
	v_mad_u32_u24 v29, v129, s33, v29
	v_add_u32_e32 v33, v128, v29
	ds_write_b32 v33, v30
	v_mov_b32_e32 v30, 0x1f3b0
	v_mad_u32_u24 v30, v129, s33, v30
	v_add_u32_e32 v33, v128, v30
	ds_write_b32 v33, v31
	v_add_u32_e32 v31, v131, v32
	ds_write_b32 v31, v0
	v_add_u32_e32 v0, v131, v16
	ds_write_b32 v0, v1
	v_add_u32_e32 v0, v131, v17
	ds_write_b32 v0, v2
	v_add_u32_e32 v0, v131, v18
	ds_write_b32 v0, v3
	v_add_u32_e32 v0, v131, v19
	ds_write_b32 v0, v4
	v_add_u32_e32 v0, v131, v20
	ds_write_b32 v0, v5
	v_add_u32_e32 v0, v131, v21
	ds_write_b32 v0, v6
	v_add_u32_e32 v0, v131, v22
	ds_write_b32 v0, v7
	v_add_u32_e32 v0, v131, v23
	ds_write_b32 v0, v8
	v_add_u32_e32 v0, v131, v24
	ds_write_b32 v0, v9
	v_add_u32_e32 v0, v131, v25
	ds_write_b32 v0, v10
	v_add_u32_e32 v0, v131, v26
	ds_write_b32 v0, v11
	v_add_u32_e32 v0, v131, v27
	ds_write_b32 v0, v12
	v_add_u32_e32 v0, v131, v28
	ds_write_b32 v0, v13
	v_add_u32_e32 v0, v131, v29
	ds_write_b32 v0, v14
	v_add_u32_e32 v0, v131, v30
	ds_write_b32 v0, v15
.LBB0_215:
	s_bitset1_b32 s13, 7
	s_waitcnt lgkmcnt(0)
	s_barrier
	v_readlane_b32 s48, v253, 12
	v_readlane_b32 s49, v253, 13
	v_readlane_b32 s50, v253, 14
	v_readlane_b32 s51, v253, 15
	v_mov_b32_e32 v1, 0
	v_add_u32_e32 v50, s13, v179
	v_ashrrev_i32_e32 v51, 31, v50
	v_lshlrev_b64 v[2:3], 12, v[50:51]
	v_lshl_add_u64 v[2:3], v[134:135], 0, v[2:3]
	v_add_u32_e32 v54, s13, v243
	v_ashrrev_i32_e32 v55, 31, v54
	v_lshlrev_b64 v[4:5], 12, v[54:55]
	v_lshl_add_u64 v[4:5], v[134:135], 0, v[4:5]
	v_add_u32_e32 v58, s13, v244
	v_ashrrev_i32_e32 v59, 31, v58
	v_lshlrev_b64 v[6:7], 12, v[58:59]
	v_lshl_add_u64 v[6:7], v[134:135], 0, v[6:7]
	v_add_u32_e32 v62, s13, v245
	v_ashrrev_i32_e32 v63, 31, v62
	v_lshlrev_b64 v[8:9], 12, v[62:63]
	v_lshl_add_u64 v[8:9], v[134:135], 0, v[8:9]
	v_add_u32_e32 v66, s13, v246
	v_ashrrev_i32_e32 v67, 31, v66
	v_lshlrev_b64 v[10:11], 12, v[66:67]
	v_lshl_add_u64 v[10:11], v[134:135], 0, v[10:11]
	v_add_u32_e32 v70, s13, v247
	v_ashrrev_i32_e32 v71, 31, v70
	v_lshlrev_b64 v[12:13], 12, v[70:71]
	v_lshl_add_u64 v[12:13], v[134:135], 0, v[12:13]
	v_add_u32_e32 v74, s13, v248
	v_ashrrev_i32_e32 v75, 31, v74
	v_lshlrev_b64 v[14:15], 12, v[74:75]
	v_lshl_add_u64 v[14:15], v[134:135], 0, v[14:15]
	v_add_u32_e32 v78, s13, v249
	v_ashrrev_i32_e32 v79, 31, v78
	v_lshlrev_b64 v[16:17], 12, v[78:79]
	v_lshl_add_u64 v[16:17], v[134:135], 0, v[16:17]
	s_and_b64 vcc, exec, s[38:39]
	s_cbranch_vccnz .Lrob0_nofi
	v_add_u32_e32 v0, 0xffffc000, v50
	v_lshlrev_b64 v[18:19], 10, v[50:51]
	v_cmp_gt_i32_e32 vcc, s2, v50
	v_lshlrev_b64 v[20:21], 12, v[0:1]
	v_lshl_add_u64 v[18:19], v[18:19], 2, s[48:49]
	v_lshl_add_u64 v[20:21], s[50:51], 0, v[20:21]
	v_cndmask_b32_e32 v21, v21, v19, vcc
	v_cndmask_b32_e32 v20, v20, v18, vcc
	v_lshl_add_u64 v[20:21], s[46:47], 2, v[20:21]
	v_lshl_add_u64 v[20:21], v[20:21], 0, v[132:133]
	v_add_u32_e32 v0, 0xffffc000, v54
	v_lshlrev_b64 v[22:23], 10, v[54:55]
	v_cmp_gt_i32_e32 vcc, s2, v54
	v_lshlrev_b64 v[24:25], 12, v[0:1]
	v_lshl_add_u64 v[22:23], v[22:23], 2, s[48:49]
	v_lshl_add_u64 v[24:25], s[50:51], 0, v[24:25]
	v_cndmask_b32_e32 v25, v25, v23, vcc
	v_cndmask_b32_e32 v24, v24, v22, vcc
	v_lshl_add_u64 v[24:25], s[46:47], 2, v[24:25]
	v_lshl_add_u64 v[24:25], v[24:25], 0, v[132:133]
	v_add_u32_e32 v0, 0xffffc000, v58
	v_lshlrev_b64 v[26:27], 10, v[58:59]
	v_cmp_gt_i32_e32 vcc, s2, v58
	v_lshlrev_b64 v[28:29], 12, v[0:1]
	v_lshl_add_u64 v[26:27], v[26:27], 2, s[48:49]
	v_lshl_add_u64 v[28:29], s[50:51], 0, v[28:29]
	v_cndmask_b32_e32 v29, v29, v27, vcc
	v_cndmask_b32_e32 v28, v28, v26, vcc
	v_lshl_add_u64 v[28:29], s[46:47], 2, v[28:29]
	v_lshl_add_u64 v[28:29], v[28:29], 0, v[132:133]
	v_add_u32_e32 v0, 0xffffc000, v62
	v_lshlrev_b64 v[30:31], 10, v[62:63]
	v_cmp_gt_i32_e32 vcc, s2, v62
	v_lshlrev_b64 v[32:33], 12, v[0:1]
	v_lshl_add_u64 v[30:31], v[30:31], 2, s[48:49]
	v_lshl_add_u64 v[32:33], s[50:51], 0, v[32:33]
	v_cndmask_b32_e32 v33, v33, v31, vcc
	v_cndmask_b32_e32 v32, v32, v30, vcc
	v_lshl_add_u64 v[32:33], s[46:47], 2, v[32:33]
	v_lshl_add_u64 v[32:33], v[32:33], 0, v[132:133]
	v_add_u32_e32 v0, 0xffffc000, v66
	v_lshlrev_b64 v[34:35], 10, v[66:67]
	v_cmp_gt_i32_e32 vcc, s2, v66
	v_lshlrev_b64 v[36:37], 12, v[0:1]
	v_lshl_add_u64 v[34:35], v[34:35], 2, s[48:49]
	v_lshl_add_u64 v[36:37], s[50:51], 0, v[36:37]
	v_cndmask_b32_e32 v37, v37, v35, vcc
	v_cndmask_b32_e32 v36, v36, v34, vcc
	v_lshl_add_u64 v[36:37], s[46:47], 2, v[36:37]
	v_lshl_add_u64 v[36:37], v[36:37], 0, v[132:133]
	v_add_u32_e32 v0, 0xffffc000, v70
	v_lshlrev_b64 v[38:39], 10, v[70:71]
	v_cmp_gt_i32_e32 vcc, s2, v70
	v_lshlrev_b64 v[40:41], 12, v[0:1]
	v_lshl_add_u64 v[38:39], v[38:39], 2, s[48:49]
	v_lshl_add_u64 v[40:41], s[50:51], 0, v[40:41]
	v_cndmask_b32_e32 v41, v41, v39, vcc
	v_cndmask_b32_e32 v40, v40, v38, vcc
	v_lshl_add_u64 v[40:41], s[46:47], 2, v[40:41]
	v_lshl_add_u64 v[40:41], v[40:41], 0, v[132:133]
	v_add_u32_e32 v0, 0xffffc000, v74
	v_lshlrev_b64 v[42:43], 10, v[74:75]
	v_cmp_gt_i32_e32 vcc, s2, v74
	v_lshlrev_b64 v[44:45], 12, v[0:1]
	v_lshl_add_u64 v[42:43], v[42:43], 2, s[48:49]
	v_lshl_add_u64 v[44:45], s[50:51], 0, v[44:45]
	v_cndmask_b32_e32 v45, v45, v43, vcc
	v_cndmask_b32_e32 v44, v44, v42, vcc
	v_lshl_add_u64 v[44:45], s[46:47], 2, v[44:45]
	v_lshl_add_u64 v[44:45], v[44:45], 0, v[132:133]
	v_add_u32_e32 v0, 0xffffc000, v78
	v_lshlrev_b64 v[46:47], 10, v[78:79]
	v_cmp_gt_i32_e32 vcc, s2, v78
	v_lshlrev_b64 v[48:49], 12, v[0:1]
	v_lshl_add_u64 v[46:47], v[46:47], 2, s[48:49]
	v_lshl_add_u64 v[48:49], s[50:51], 0, v[48:49]
	v_cndmask_b32_e32 v49, v49, v47, vcc
	v_cndmask_b32_e32 v48, v48, v46, vcc
	v_lshl_add_u64 v[48:49], s[46:47], 2, v[48:49]
	v_lshl_add_u64 v[48:49], v[48:49], 0, v[132:133]
	s_branch .Lrob0_ld
.Lrob0_nofi:
	v_mov_b64_e32 v[20:21], v[2:3]
	v_mov_b64_e32 v[24:25], v[4:5]
	v_mov_b64_e32 v[28:29], v[6:7]
	v_mov_b64_e32 v[32:33], v[8:9]
	v_mov_b64_e32 v[36:37], v[10:11]
	v_mov_b64_e32 v[40:41], v[12:13]
	v_mov_b64_e32 v[44:45], v[14:15]
	v_mov_b64_e32 v[48:49], v[16:17]
.Lrob0_ld:
	global_load_dwordx4 v[18:21], v[20:21], off
	s_nop 0
	global_load_dwordx4 v[22:25], v[24:25], off
	s_nop 0
	global_load_dwordx4 v[26:29], v[28:29], off
	s_nop 0
	global_load_dwordx4 v[30:33], v[32:33], off
	s_nop 0
	global_load_dwordx4 v[34:37], v[36:37], off
	s_nop 0
	global_load_dwordx4 v[38:41], v[40:41], off
	s_nop 0
	global_load_dwordx4 v[42:45], v[44:45], off
	s_nop 0
	global_load_dwordx4 v[46:49], v[48:49], off
	s_nop 0
	ds_read_b128 v[50:53], v200
	ds_read_b128 v[54:57], v201
	ds_read_b128 v[58:61], v242
	ds_read_b128 v[62:65], v238
	ds_read_b128 v[66:69], v205
	ds_read_b128 v[70:73], v209
	ds_read_b128 v[74:77], v213
	ds_read_b128 v[78:81], v217
	s_waitcnt vmcnt(7) lgkmcnt(7)
	v_pk_add_f32 v[50:51], v[50:51], v[18:19]
	v_pk_add_f32 v[52:53], v[52:53], v[20:21]
	global_store_dwordx4 v[2:3], v[50:53], off
	s_waitcnt vmcnt(7) lgkmcnt(6)
	v_pk_add_f32 v[54:55], v[54:55], v[22:23]
	v_pk_add_f32 v[56:57], v[56:57], v[24:25]
	global_store_dwordx4 v[4:5], v[54:57], off
	s_waitcnt vmcnt(7) lgkmcnt(5)
	v_pk_add_f32 v[58:59], v[58:59], v[26:27]
	v_pk_add_f32 v[60:61], v[60:61], v[28:29]
	global_store_dwordx4 v[6:7], v[58:61], off
	s_waitcnt vmcnt(7) lgkmcnt(4)
	v_pk_add_f32 v[62:63], v[62:63], v[30:31]
	v_pk_add_f32 v[64:65], v[64:65], v[32:33]
	global_store_dwordx4 v[8:9], v[62:65], off
	s_waitcnt vmcnt(7) lgkmcnt(3)
	v_pk_add_f32 v[66:67], v[66:67], v[34:35]
	v_pk_add_f32 v[68:69], v[68:69], v[36:37]
	global_store_dwordx4 v[10:11], v[66:69], off
	s_waitcnt vmcnt(7) lgkmcnt(2)
	v_pk_add_f32 v[70:71], v[70:71], v[38:39]
	v_pk_add_f32 v[72:73], v[72:73], v[40:41]
	global_store_dwordx4 v[12:13], v[70:73], off
	s_waitcnt vmcnt(7) lgkmcnt(1)
	v_pk_add_f32 v[74:75], v[74:75], v[42:43]
	v_pk_add_f32 v[76:77], v[76:77], v[44:45]
	global_store_dwordx4 v[14:15], v[74:77], off
	s_waitcnt vmcnt(7) lgkmcnt(0)
	v_pk_add_f32 v[78:79], v[78:79], v[46:47]
	v_pk_add_f32 v[80:81], v[80:81], v[48:49]
	global_store_dwordx4 v[16:17], v[78:81], off
	v_add_u32_e32 v50, s13, v250
	v_ashrrev_i32_e32 v51, 31, v50
	v_lshlrev_b64 v[2:3], 12, v[50:51]
	v_lshl_add_u64 v[2:3], v[134:135], 0, v[2:3]
	v_add_u32_e32 v54, s13, v251
	v_ashrrev_i32_e32 v55, 31, v54
	v_lshlrev_b64 v[4:5], 12, v[54:55]
	v_lshl_add_u64 v[4:5], v[134:135], 0, v[4:5]
	v_add_u32_e32 v58, s13, v241
	v_ashrrev_i32_e32 v59, 31, v58
	v_lshlrev_b64 v[6:7], 12, v[58:59]
	v_lshl_add_u64 v[6:7], v[134:135], 0, v[6:7]
	v_add_u32_e32 v62, s13, v191
	v_ashrrev_i32_e32 v63, 31, v62
	v_lshlrev_b64 v[8:9], 12, v[62:63]
	v_lshl_add_u64 v[8:9], v[134:135], 0, v[8:9]
	v_add_u32_e32 v66, s13, v192
	v_ashrrev_i32_e32 v67, 31, v66
	v_lshlrev_b64 v[10:11], 12, v[66:67]
	v_lshl_add_u64 v[10:11], v[134:135], 0, v[10:11]
	v_add_u32_e32 v70, s13, v197
	v_ashrrev_i32_e32 v71, 31, v70
	v_lshlrev_b64 v[12:13], 12, v[70:71]
	v_lshl_add_u64 v[12:13], v[134:135], 0, v[12:13]
	v_add_u32_e32 v74, s13, v198
	v_ashrrev_i32_e32 v75, 31, v74
	v_lshlrev_b64 v[14:15], 12, v[74:75]
	v_lshl_add_u64 v[14:15], v[134:135], 0, v[14:15]
	v_add_u32_e32 v78, s13, v199
	v_ashrrev_i32_e32 v79, 31, v78
	v_lshlrev_b64 v[16:17], 12, v[78:79]
	v_lshl_add_u64 v[16:17], v[134:135], 0, v[16:17]
	s_and_b64 vcc, exec, s[38:39]
	s_cbranch_vccnz .Lrob1_nofi
	v_add_u32_e32 v0, 0xffffc000, v50
	v_lshlrev_b64 v[18:19], 10, v[50:51]
	v_cmp_gt_i32_e32 vcc, s2, v50
	v_lshlrev_b64 v[20:21], 12, v[0:1]
	v_lshl_add_u64 v[18:19], v[18:19], 2, s[48:49]
	v_lshl_add_u64 v[20:21], s[50:51], 0, v[20:21]
	v_cndmask_b32_e32 v21, v21, v19, vcc
	v_cndmask_b32_e32 v20, v20, v18, vcc
	v_lshl_add_u64 v[20:21], s[46:47], 2, v[20:21]
	v_lshl_add_u64 v[20:21], v[20:21], 0, v[132:133]
	v_add_u32_e32 v0, 0xffffc000, v54
	v_lshlrev_b64 v[22:23], 10, v[54:55]
	v_cmp_gt_i32_e32 vcc, s2, v54
	v_lshlrev_b64 v[24:25], 12, v[0:1]
	v_lshl_add_u64 v[22:23], v[22:23], 2, s[48:49]
	v_lshl_add_u64 v[24:25], s[50:51], 0, v[24:25]
	v_cndmask_b32_e32 v25, v25, v23, vcc
	v_cndmask_b32_e32 v24, v24, v22, vcc
	v_lshl_add_u64 v[24:25], s[46:47], 2, v[24:25]
	v_lshl_add_u64 v[24:25], v[24:25], 0, v[132:133]
	v_add_u32_e32 v0, 0xffffc000, v58
	v_lshlrev_b64 v[26:27], 10, v[58:59]
	v_cmp_gt_i32_e32 vcc, s2, v58
	v_lshlrev_b64 v[28:29], 12, v[0:1]
	v_lshl_add_u64 v[26:27], v[26:27], 2, s[48:49]
	v_lshl_add_u64 v[28:29], s[50:51], 0, v[28:29]
	v_cndmask_b32_e32 v29, v29, v27, vcc
	v_cndmask_b32_e32 v28, v28, v26, vcc
	v_lshl_add_u64 v[28:29], s[46:47], 2, v[28:29]
	v_lshl_add_u64 v[28:29], v[28:29], 0, v[132:133]
	v_add_u32_e32 v0, 0xffffc000, v62
	v_lshlrev_b64 v[30:31], 10, v[62:63]
	v_cmp_gt_i32_e32 vcc, s2, v62
	v_lshlrev_b64 v[32:33], 12, v[0:1]
	v_lshl_add_u64 v[30:31], v[30:31], 2, s[48:49]
	v_lshl_add_u64 v[32:33], s[50:51], 0, v[32:33]
	v_cndmask_b32_e32 v33, v33, v31, vcc
	v_cndmask_b32_e32 v32, v32, v30, vcc
	v_lshl_add_u64 v[32:33], s[46:47], 2, v[32:33]
	v_lshl_add_u64 v[32:33], v[32:33], 0, v[132:133]
	v_add_u32_e32 v0, 0xffffc000, v66
	v_lshlrev_b64 v[34:35], 10, v[66:67]
	v_cmp_gt_i32_e32 vcc, s2, v66
	v_lshlrev_b64 v[36:37], 12, v[0:1]
	v_lshl_add_u64 v[34:35], v[34:35], 2, s[48:49]
	v_lshl_add_u64 v[36:37], s[50:51], 0, v[36:37]
	v_cndmask_b32_e32 v37, v37, v35, vcc
	v_cndmask_b32_e32 v36, v36, v34, vcc
	v_lshl_add_u64 v[36:37], s[46:47], 2, v[36:37]
	v_lshl_add_u64 v[36:37], v[36:37], 0, v[132:133]
	v_add_u32_e32 v0, 0xffffc000, v70
	v_lshlrev_b64 v[38:39], 10, v[70:71]
	v_cmp_gt_i32_e32 vcc, s2, v70
	v_lshlrev_b64 v[40:41], 12, v[0:1]
	v_lshl_add_u64 v[38:39], v[38:39], 2, s[48:49]
	v_lshl_add_u64 v[40:41], s[50:51], 0, v[40:41]
	v_cndmask_b32_e32 v41, v41, v39, vcc
	v_cndmask_b32_e32 v40, v40, v38, vcc
	v_lshl_add_u64 v[40:41], s[46:47], 2, v[40:41]
	v_lshl_add_u64 v[40:41], v[40:41], 0, v[132:133]
	v_add_u32_e32 v0, 0xffffc000, v74
	v_lshlrev_b64 v[42:43], 10, v[74:75]
	v_cmp_gt_i32_e32 vcc, s2, v74
	v_lshlrev_b64 v[44:45], 12, v[0:1]
	v_lshl_add_u64 v[42:43], v[42:43], 2, s[48:49]
	v_lshl_add_u64 v[44:45], s[50:51], 0, v[44:45]
	v_cndmask_b32_e32 v45, v45, v43, vcc
	v_cndmask_b32_e32 v44, v44, v42, vcc
	v_lshl_add_u64 v[44:45], s[46:47], 2, v[44:45]
	v_lshl_add_u64 v[44:45], v[44:45], 0, v[132:133]
	v_add_u32_e32 v0, 0xffffc000, v78
	v_lshlrev_b64 v[46:47], 10, v[78:79]
	v_cmp_gt_i32_e32 vcc, s2, v78
	v_lshlrev_b64 v[48:49], 12, v[0:1]
	v_lshl_add_u64 v[46:47], v[46:47], 2, s[48:49]
	v_lshl_add_u64 v[48:49], s[50:51], 0, v[48:49]
	v_cndmask_b32_e32 v49, v49, v47, vcc
	v_cndmask_b32_e32 v48, v48, v46, vcc
	v_lshl_add_u64 v[48:49], s[46:47], 2, v[48:49]
	v_lshl_add_u64 v[48:49], v[48:49], 0, v[132:133]
	s_branch .Lrob1_ld

.Lrob1_ld:
	global_load_dwordx4 v[18:21], v[20:21], off
	s_nop 0
	global_load_dwordx4 v[22:25], v[24:25], off
	s_nop 0
	global_load_dwordx4 v[26:29], v[28:29], off
	s_nop 0
	global_load_dwordx4 v[30:33], v[32:33], off
	s_nop 0
	global_load_dwordx4 v[34:37], v[36:37], off
	s_nop 0
	global_load_dwordx4 v[38:41], v[40:41], off
	s_nop 0
	global_load_dwordx4 v[42:45], v[44:45], off
	s_nop 0
	global_load_dwordx4 v[46:49], v[48:49], off
	s_nop 0
	ds_read_b128 v[50:53], v221
	ds_read_b128 v[54:57], v225
	ds_read_b128 v[58:61], v229
	ds_read_b128 v[62:65], v233
	ds_read_b128 v[66:69], v206
	ds_read_b128 v[70:73], v207
	ds_read_b128 v[74:77], v208
	ds_read_b128 v[78:81], v210
	s_waitcnt vmcnt(7) lgkmcnt(7)
	v_pk_add_f32 v[50:51], v[50:51], v[18:19]
	v_pk_add_f32 v[52:53], v[52:53], v[20:21]
	global_store_dwordx4 v[2:3], v[50:53], off
	s_waitcnt vmcnt(7) lgkmcnt(6)
	v_pk_add_f32 v[54:55], v[54:55], v[22:23]
	v_pk_add_f32 v[56:57], v[56:57], v[24:25]
	global_store_dwordx4 v[4:5], v[54:57], off
	s_waitcnt vmcnt(7) lgkmcnt(5)
	v_pk_add_f32 v[58:59], v[58:59], v[26:27]
	v_pk_add_f32 v[60:61], v[60:61], v[28:29]
	global_store_dwordx4 v[6:7], v[58:61], off
	s_waitcnt vmcnt(7) lgkmcnt(4)
	v_pk_add_f32 v[62:63], v[62:63], v[30:31]
	v_pk_add_f32 v[64:65], v[64:65], v[32:33]
	global_store_dwordx4 v[8:9], v[62:65], off
	s_waitcnt vmcnt(7) lgkmcnt(3)
	v_pk_add_f32 v[66:67], v[66:67], v[34:35]
	v_pk_add_f32 v[68:69], v[68:69], v[36:37]
	global_store_dwordx4 v[10:11], v[66:69], off
	s_waitcnt vmcnt(7) lgkmcnt(2)
	v_pk_add_f32 v[70:71], v[70:71], v[38:39]
	v_pk_add_f32 v[72:73], v[72:73], v[40:41]
	global_store_dwordx4 v[12:13], v[70:73], off
	s_waitcnt vmcnt(7) lgkmcnt(1)
	v_pk_add_f32 v[74:75], v[74:75], v[42:43]
	v_pk_add_f32 v[76:77], v[76:77], v[44:45]
	global_store_dwordx4 v[14:15], v[74:77], off
	s_waitcnt vmcnt(7) lgkmcnt(0)
	v_pk_add_f32 v[78:79], v[78:79], v[46:47]
	v_pk_add_f32 v[80:81], v[80:81], v[48:49]
	global_store_dwordx4 v[16:17], v[78:81], off
	s_branch .LBB0_166

.LBB0_574:
	s_cmpk_gt_i32 s10, 0xd7f
	s_mov_b64 s[4:5], -1
	s_cbranch_scc0 .LBB0_588
	s_cmpk_gt_u32 s10, 0xf7f
	s_cbranch_scc0 .LBB0_585
	s_cmpk_gt_u32 s10, 0x117f
	s_cbranch_scc0 .LBB0_582
	s_cmpk_gt_u32 s10, 0x1c7f
	s_cbranch_scc0 .LBB0_579
	s_add_i32 s8, s10, 0xffffe380
	s_cmpk_gt_u32 s8, 0x2bf
	s_cselect_b64 s[4:5], -1, 0
	s_and_b64 s[6:7], s[4:5], exec
	v_readlane_b32 s40, v254, 38
	s_cselect_b32 s6, 0xb00000, 0
	v_readlane_b32 s52, v254, 50
	v_readlane_b32 s53, v254, 51
	s_add_u32 s11, s52, s6
	s_addc_u32 s14, s53, 0
	s_and_b64 s[6:7], s[4:5], exec
	s_cselect_b32 s6, 0x580000, 0
	v_readlane_b32 s2, v253, 32
	s_add_u32 s6, s2, s6
	v_readlane_b32 s2, v253, 33
	s_addc_u32 s7, s2, 0
	s_and_b64 s[4:5], s[4:5], exec
	s_cselect_b32 s4, 0xfffffd40, 0
	s_add_i32 s5, s4, s8
	s_bfe_u32 s4, s5, 0x4001b
	s_add_i32 s4, s5, s4
	s_sext_i32_i16 s4, s4
	s_ashr_i32 s8, s4, 4
	s_lshl_b32 s4, s8, 6
	s_lshl_b32 s8, s8, 10
	s_lshl_b32 s5, s5, 6
	s_sub_i32 s8, s5, s8
	v_mov_b32_e32 v8, v190
	s_ashr_i32 s9, s8, 31
	s_lshl_b64 s[12:13], s[8:9], 2
	v_ashrrev_i32_e32 v6, 6, v8
	s_add_u32 s12, s11, s12
	v_lshlrev_b32_e32 v0, 2, v8
	v_add_u32_e32 v2, s4, v6
	s_addc_u32 s13, s14, s13
	v_and_b32_e32 v176, 0xfc, v0
	v_ashrrev_i32_e32 v3, 31, v2
	v_lshl_add_u64 v[0:1], s[12:13], 0, v[176:177]
	v_lshlrev_b64 v[4:5], 12, v[2:3]
	v_lshl_add_u64 v[4:5], v[0:1], 0, v[4:5]
	s_barrier
	global_load_dword v10, v[4:5], off
	v_mad_u64_u32 v[4:5], s[12:13], v6, s15, v[176:177]
	v_add_u32_e32 v6, 8, v2
	v_ashrrev_i32_e32 v7, 31, v6
	v_lshlrev_b64 v[6:7], 12, v[6:7]
	v_lshl_add_u64 v[6:7], v[0:1], 0, v[6:7]
	v_ashrrev_i32_e32 v9, 3, v8
	s_movk_i32 s2, 0x1600
	s_ashr_i32 s5, s4, 31
	v_readlane_b32 s41, v254, 39
	v_readlane_b32 s42, v254, 40
	v_readlane_b32 s43, v254, 41
	v_readlane_b32 s44, v254, 42
	v_readlane_b32 s45, v254, 43
	v_readlane_b32 s46, v254, 44
	v_readlane_b32 s47, v254, 45
	v_readlane_b32 s48, v254, 46
	v_readlane_b32 s49, v254, 47
	v_readlane_b32 s50, v254, 48
	v_readlane_b32 s51, v254, 49
	v_readlane_b32 s54, v254, 52
	v_readlane_b32 s55, v254, 53
	s_movk_i32 s14, 0x4000
	global_load_dword v11, v[6:7], off
	v_add_u32_e32 v6, 16, v2
	v_ashrrev_i32_e32 v7, 31, v6
	v_lshlrev_b64 v[6:7], 12, v[6:7]
	v_lshl_add_u64 v[6:7], v[0:1], 0, v[6:7]
	global_load_dword v12, v[6:7], off
	v_add_u32_e32 v6, 24, v2
	v_ashrrev_i32_e32 v7, 31, v6
	v_lshlrev_b64 v[6:7], 12, v[6:7]
	v_lshl_add_u64 v[6:7], v[0:1], 0, v[6:7]
	global_load_dword v13, v[6:7], off
	v_add_u32_e32 v6, 32, v2
	v_ashrrev_i32_e32 v7, 31, v6
	v_lshlrev_b64 v[6:7], 12, v[6:7]
	v_lshl_add_u64 v[6:7], v[0:1], 0, v[6:7]
	global_load_dword v14, v[6:7], off
	v_add_u32_e32 v6, 40, v2
	v_ashrrev_i32_e32 v7, 31, v6
	v_lshlrev_b64 v[6:7], 12, v[6:7]
	v_lshl_add_u64 v[6:7], v[0:1], 0, v[6:7]
	global_load_dword v15, v[6:7], off
	v_add_u32_e32 v6, 48, v2
	v_ashrrev_i32_e32 v7, 31, v6
	v_lshlrev_b64 v[6:7], 12, v[6:7]
	v_lshl_add_u64 v[6:7], v[0:1], 0, v[6:7]
	v_add_u32_e32 v2, 56, v2
	global_load_dword v16, v[6:7], off
	v_ashrrev_i32_e32 v3, 31, v2
	v_lshlrev_b64 v[2:3], 12, v[2:3]
	v_lshl_add_u64 v[0:1], v[0:1], 0, v[2:3]
	global_load_dword v17, v[0:1], off
	s_waitcnt vmcnt(7)
	ds_write_b32 v4, v10
	s_waitcnt vmcnt(6)
	ds_write_b32 v4, v11 offset:2080
	s_waitcnt vmcnt(5)
	ds_write_b32 v4, v12 offset:4160
	s_waitcnt vmcnt(4)
	ds_write_b32 v4, v13 offset:6240
	s_waitcnt vmcnt(3)
	ds_write_b32 v4, v14 offset:8320
	s_waitcnt vmcnt(2)
	ds_write_b32 v4, v15 offset:10400
	s_waitcnt vmcnt(1)
	ds_write_b32 v4, v16 offset:12480
	s_waitcnt vmcnt(0)
	ds_write_b32 v4, v17 offset:14560
	v_lshlrev_b32_e32 v0, 3, v8
	v_and_b32_e32 v176, 56, v0
	v_mul_u32_u24_e32 v0, 0x104, v176
	v_lshl_add_u32 v4, v9, 2, v0
	v_add_u32_e32 v6, 0x400, v4
	s_waitcnt lgkmcnt(0)
	s_barrier
	ds_read2_b32 v[0:1], v4 offset1:65
	ds_read2_b32 v[2:3], v4 offset0:130 offset1:195
	ds_read2_b32 v[4:5], v6 offset0:4 offset1:69
	ds_read2_b32 v[6:7], v6 offset0:134 offset1:199
	s_waitcnt lgkmcnt(3)
	v_cvt_pk_bf16_f32 v0, v0, v1
	s_waitcnt lgkmcnt(2)
	v_cvt_pk_bf16_f32 v1, v2, v3
	s_waitcnt lgkmcnt(1)
	v_cvt_pk_bf16_f32 v2, v4, v5
	s_waitcnt lgkmcnt(0)
	v_cvt_pk_bf16_f32 v3, v6, v7
	v_add_u32_e32 v6, s8, v9
	v_mov_b64_e32 v[4:5], s[6:7]
	v_mad_i64_i32 v[4:5], s[6:7], v6, s2, v[4:5]
	v_lshl_add_u64 v[4:5], s[4:5], 1, v[4:5]
	s_mov_b64 s[4:5], 0
.LBB0_579:
	s_andn2_b64 vcc, exec, s[4:5]
	s_cbranch_vccnz .LBB0_581
	s_add_i32 s8, s10, 0xffffee80
	s_cmpk_gt_u32 s8, 0x57f
	s_cselect_b64 s[4:5], -1, 0
	s_and_b64 s[6:7], s[4:5], exec
	v_readlane_b32 s40, v254, 38
	s_cselect_b32 s6, 0x1600000, 0
	v_readlane_b32 s46, v254, 44
	v_readlane_b32 s47, v254, 45
	s_add_u32 s11, s46, s6
	s_addc_u32 s14, s47, 0
	s_and_b64 s[6:7], s[4:5], exec
	s_cselect_b32 s6, 0xb00000, 0
	v_readlane_b32 s2, v253, 35
	s_add_u32 s6, s2, s6
	v_readlane_b32 s2, v253, 36
	s_addc_u32 s7, s2, 0
	s_and_b64 s[4:5], s[4:5], exec
	s_cselect_b32 s4, 0xfffffa80, 0
	s_add_i32 s4, s4, s8
	s_mul_i32 s5, s4, 0xba3
	s_lshr_b32 s8, s5, 31
	s_ashr_i32 s5, s5, 18
	s_add_i32 s5, s5, s8
	s_sext_i32_i16 s5, s5
	s_mul_i32 s8, s5, 0xffffffa8
	s_add_i32 s8, s8, s4
	s_lshl_b32 s8, s8, 6
	s_ashr_i32 s9, s8, 31
	v_mov_b32_e32 v6, v190
	s_lshl_b32 s4, s5, 6
	s_lshl_b64 s[12:13], s[8:9], 2
	s_add_u32 s12, s11, s12
	v_lshlrev_b32_e32 v0, 2, v6
	v_ashrrev_i32_e32 v4, 6, v6
	s_addc_u32 s13, s14, s13
	v_and_b32_e32 v176, 0xfc, v0
	v_lshl_add_u64 v[0:1], s[12:13], 0, v[176:177]
	v_add_u32_e32 v7, s4, v4
	s_movk_i32 s2, 0x5800
	v_mad_i64_i32 v[2:3], s[12:13], v7, s2, v[0:1]
	s_barrier
	global_load_dword v10, v[2:3], off
	v_mad_u64_u32 v[2:3], s[12:13], v4, s15, v[176:177]
	v_add_u32_e32 v3, 8, v7
	v_ashrrev_i32_e32 v8, 3, v6
	s_ashr_i32 s5, s4, 31
	s_movk_i32 s14, 0x4000
	v_readlane_b32 s41, v254, 39
	v_readlane_b32 s42, v254, 40
	v_readlane_b32 s43, v254, 41
	v_readlane_b32 s44, v254, 42
	v_readlane_b32 s45, v254, 43
	v_readlane_b32 s48, v254, 46
	v_readlane_b32 s49, v254, 47
	v_readlane_b32 s50, v254, 48
	v_readlane_b32 s51, v254, 49
	v_readlane_b32 s52, v254, 50
	v_readlane_b32 s53, v254, 51
	v_readlane_b32 s54, v254, 52
	v_readlane_b32 s55, v254, 53
	v_mad_i64_i32 v[4:5], s[12:13], v3, s2, v[0:1]
	global_load_dword v11, v[4:5], off
	v_add_u32_e32 v3, 16, v7
	v_mad_i64_i32 v[4:5], s[12:13], v3, s2, v[0:1]
	global_load_dword v12, v[4:5], off
	v_add_u32_e32 v3, 24, v7
	v_mad_i64_i32 v[4:5], s[12:13], v3, s2, v[0:1]
	global_load_dword v13, v[4:5], off
	v_add_u32_e32 v3, 32, v7
	v_mad_i64_i32 v[4:5], s[12:13], v3, s2, v[0:1]
	global_load_dword v14, v[4:5], off
	v_add_u32_e32 v3, 40, v7
	v_mad_i64_i32 v[4:5], s[12:13], v3, s2, v[0:1]
	global_load_dword v15, v[4:5], off
	v_add_u32_e32 v3, 48, v7
	v_mad_i64_i32 v[4:5], s[12:13], v3, s2, v[0:1]
	global_load_dword v16, v[4:5], off
	v_add_u32_e32 v3, 56, v7
	v_mad_i64_i32 v[0:1], s[12:13], v3, s2, v[0:1]
	global_load_dword v17, v[0:1], off
	s_waitcnt vmcnt(7)
	ds_write_b32 v2, v10
	s_waitcnt vmcnt(6)
	ds_write_b32 v2, v11 offset:2080
	s_waitcnt vmcnt(5)
	ds_write_b32 v2, v12 offset:4160
	s_waitcnt vmcnt(4)
	ds_write_b32 v2, v13 offset:6240
	s_waitcnt vmcnt(3)
	ds_write_b32 v2, v14 offset:8320
	s_waitcnt vmcnt(2)
	ds_write_b32 v2, v15 offset:10400
	s_waitcnt vmcnt(1)
	ds_write_b32 v2, v16 offset:12480
	s_waitcnt vmcnt(0)
	ds_write_b32 v2, v17 offset:14560
	v_lshlrev_b32_e32 v0, 3, v6
	v_and_b32_e32 v176, 56, v0
	v_mul_u32_u24_e32 v0, 0x104, v176
	v_lshl_add_u32 v4, v8, 2, v0
	s_waitcnt lgkmcnt(0)
	s_barrier
	ds_read2_b32 v[0:1], v4 offset1:65
	ds_read2_b32 v[2:3], v4 offset0:130 offset1:195
	v_add_u32_e32 v6, 0x400, v4
	ds_read2_b32 v[4:5], v6 offset0:4 offset1:69
	ds_read2_b32 v[6:7], v6 offset0:134 offset1:199
	s_waitcnt lgkmcnt(3)
	v_cvt_pk_bf16_f32 v0, v0, v1
	s_waitcnt lgkmcnt(2)
	v_cvt_pk_bf16_f32 v1, v2, v3
	s_waitcnt lgkmcnt(1)
	v_cvt_pk_bf16_f32 v2, v4, v5
	v_add_u32_e32 v4, s8, v8
	v_ashrrev_i32_e32 v5, 31, v4
	v_lshlrev_b64 v[4:5], 11, v[4:5]
	v_lshl_add_u64 v[4:5], s[6:7], 0, v[4:5]
	s_waitcnt lgkmcnt(0)
	v_cvt_pk_bf16_f32 v3, v6, v7
	v_lshl_add_u64 v[4:5], s[4:5], 1, v[4:5]

.LBB0_582:
	s_andn2_b64 vcc, exec, s[4:5]
	s_cbranch_vccnz .LBB0_584
	s_add_i32 s6, s10, 0xfffff080
	s_lshr_b32 s36, s6, 8
	v_readlane_b32 s40, v254, 38
	s_lshl_b64 s[4:5], s[36:37], 22
	v_readlane_b32 s42, v254, 40
	v_readlane_b32 s43, v254, 41
	s_add_u32 s9, s42, s4
	s_addc_u32 s11, s43, s5
	s_lshl_b64 s[4:5], s[36:37], 21
	v_readlane_b32 s2, v253, 37
	s_add_u32 s4, s2, s4
	v_readlane_b32 s2, v253, 38
	s_addc_u32 s5, s2, s5
	s_bfe_u32 s8, s6, 0x40004
	s_lshl_b32 s6, s6, 6
	s_lshl_b32 s7, s8, 10
	s_and_b32 s6, s6, 0x3fc0
	s_sub_i32 s6, s6, s7
	v_mov_b32_e32 v8, v190
	s_ashr_i32 s7, s6, 31
	s_lshl_b64 s[12:13], s[6:7], 2
	v_ashrrev_i32_e32 v6, 6, v8
	s_add_u32 s12, s9, s12
	v_lshlrev_b32_e32 v0, 2, v8
	v_lshl_add_u32 v2, s8, 6, v6
	s_addc_u32 s13, s11, s13
	v_and_b32_e32 v176, 0xfc, v0
	v_ashrrev_i32_e32 v3, 31, v2
	v_lshl_add_u64 v[0:1], s[12:13], 0, v[176:177]
	v_lshlrev_b64 v[4:5], 12, v[2:3]
	v_lshl_add_u64 v[4:5], v[0:1], 0, v[4:5]
	s_barrier
	global_load_dword v10, v[4:5], off
	v_mad_u64_u32 v[4:5], s[12:13], v6, s15, v[176:177]
	v_add_u32_e32 v6, 8, v2
	v_ashrrev_i32_e32 v7, 31, v6
	v_lshlrev_b64 v[6:7], 12, v[6:7]
	v_lshl_add_u64 v[6:7], v[0:1], 0, v[6:7]
	v_ashrrev_i32_e32 v9, 3, v8
	s_lshl_b32 s36, s8, 7
	v_readlane_b32 s41, v254, 39
	v_readlane_b32 s44, v254, 42
	v_readlane_b32 s45, v254, 43
	v_readlane_b32 s46, v254, 44
	v_readlane_b32 s47, v254, 45
	v_readlane_b32 s48, v254, 46
	v_readlane_b32 s49, v254, 47
	v_readlane_b32 s50, v254, 48
	v_readlane_b32 s51, v254, 49
	v_readlane_b32 s52, v254, 50
	v_readlane_b32 s53, v254, 51
	v_readlane_b32 s54, v254, 52
	v_readlane_b32 s55, v254, 53
	global_load_dword v11, v[6:7], off
	v_add_u32_e32 v6, 16, v2
	v_ashrrev_i32_e32 v7, 31, v6
	v_lshlrev_b64 v[6:7], 12, v[6:7]
	v_lshl_add_u64 v[6:7], v[0:1], 0, v[6:7]
	global_load_dword v12, v[6:7], off
	v_add_u32_e32 v6, 24, v2
	v_ashrrev_i32_e32 v7, 31, v6
	v_lshlrev_b64 v[6:7], 12, v[6:7]
	v_lshl_add_u64 v[6:7], v[0:1], 0, v[6:7]
	global_load_dword v13, v[6:7], off
	v_add_u32_e32 v6, 32, v2
	v_ashrrev_i32_e32 v7, 31, v6
	v_lshlrev_b64 v[6:7], 12, v[6:7]
	v_lshl_add_u64 v[6:7], v[0:1], 0, v[6:7]
	global_load_dword v14, v[6:7], off
	v_add_u32_e32 v6, 40, v2
	v_ashrrev_i32_e32 v7, 31, v6
	v_lshlrev_b64 v[6:7], 12, v[6:7]
	v_lshl_add_u64 v[6:7], v[0:1], 0, v[6:7]
	global_load_dword v15, v[6:7], off
	v_add_u32_e32 v6, 48, v2
	v_ashrrev_i32_e32 v7, 31, v6
	v_lshlrev_b64 v[6:7], 12, v[6:7]
	v_lshl_add_u64 v[6:7], v[0:1], 0, v[6:7]
	v_add_u32_e32 v2, 56, v2
	global_load_dword v16, v[6:7], off
	v_ashrrev_i32_e32 v3, 31, v2
	v_lshlrev_b64 v[2:3], 12, v[2:3]
	v_lshl_add_u64 v[0:1], v[0:1], 0, v[2:3]
	global_load_dword v17, v[0:1], off
	s_waitcnt vmcnt(7)
	ds_write_b32 v4, v10
	s_waitcnt vmcnt(6)
	ds_write_b32 v4, v11 offset:2080
	s_waitcnt vmcnt(5)
	ds_write_b32 v4, v12 offset:4160
	s_waitcnt vmcnt(4)
	ds_write_b32 v4, v13 offset:6240
	s_waitcnt vmcnt(3)
	ds_write_b32 v4, v14 offset:8320
	s_waitcnt vmcnt(2)
	ds_write_b32 v4, v15 offset:10400
	s_waitcnt vmcnt(1)
	ds_write_b32 v4, v16 offset:12480
	s_waitcnt vmcnt(0)
	ds_write_b32 v4, v17 offset:14560
	v_lshlrev_b32_e32 v0, 3, v8
	v_and_b32_e32 v176, 56, v0
	v_mul_u32_u24_e32 v0, 0x104, v176
	v_lshl_add_u32 v4, v9, 2, v0
	s_waitcnt lgkmcnt(0)
	s_barrier
	ds_read2_b32 v[0:1], v4 offset1:65
	ds_read2_b32 v[2:3], v4 offset0:130 offset1:195
	v_add_u32_e32 v6, 0x400, v4
	ds_read2_b32 v[4:5], v6 offset0:4 offset1:69
	ds_read2_b32 v[6:7], v6 offset0:134 offset1:199
	s_waitcnt lgkmcnt(3)
	v_cvt_pk_bf16_f32 v0, v0, v1
	s_waitcnt lgkmcnt(2)
	v_cvt_pk_bf16_f32 v1, v2, v3
	s_waitcnt lgkmcnt(1)
	v_cvt_pk_bf16_f32 v2, v4, v5
	v_add_u32_e32 v4, s6, v9
	v_ashrrev_i32_e32 v5, 31, v4
	v_lshlrev_b64 v[4:5], 11, v[4:5]
	v_lshl_add_u64 v[4:5], s[4:5], 0, v[4:5]
	s_waitcnt lgkmcnt(0)
	v_cvt_pk_bf16_f32 v3, v6, v7
	v_lshl_add_u64 v[4:5], v[4:5], 0, s[36:37]

.LBB0_585:
	s_andn2_b64 vcc, exec, s[4:5]
	s_cbranch_vccnz .LBB0_587
	s_add_i32 s4, s10, 0xfffff280
	s_lshr_b32 s36, s4, 6
	s_lshl_b64 s[4:5], s[36:37], 20
	v_readlane_b32 s40, v254, 38
	v_readlane_b32 s41, v254, 39
	s_add_u32 s8, s40, s4
	s_addc_u32 s9, s41, s5
	s_lshl_b64 s[4:5], s[36:37], 19
	v_readlane_b32 s2, v253, 41
	s_add_u32 s4, s2, s4
	v_readlane_b32 s2, v253, 42
	s_addc_u32 s5, s2, s5
	s_lshl_b32 s7, s10, 6
	v_mov_b32_e32 v8, v190
	s_lshl_b32 s6, s10, 2
	s_and_b32 s7, s7, 0x3c0
	s_and_b32 s6, s6, 0xc0
	v_ashrrev_i32_e32 v6, 6, v8
	s_lshl_b32 s11, s7, 2
	s_add_u32 s8, s8, s11
	v_lshlrev_b32_e32 v0, 2, v8
	v_add_u32_e32 v2, s6, v6
	s_addc_u32 s9, s9, 0
	v_and_b32_e32 v176, 0xfc, v0
	v_ashrrev_i32_e32 v3, 31, v2
	v_lshl_add_u64 v[0:1], s[8:9], 0, v[176:177]
	v_lshlrev_b64 v[4:5], 12, v[2:3]
	v_lshl_add_u64 v[4:5], v[0:1], 0, v[4:5]
	s_barrier
	global_load_dword v10, v[4:5], off
	v_mad_u64_u32 v[4:5], s[8:9], v6, s15, v[176:177]
	v_add_u32_e32 v6, 8, v2
	v_ashrrev_i32_e32 v7, 31, v6
	v_lshlrev_b64 v[6:7], 12, v[6:7]
	v_lshl_add_u64 v[6:7], v[0:1], 0, v[6:7]
	v_ashrrev_i32_e32 v9, 3, v8
	s_lshl_b32 s36, s6, 1
	v_readlane_b32 s42, v254, 40
	v_readlane_b32 s43, v254, 41
	v_readlane_b32 s44, v254, 42
	v_readlane_b32 s45, v254, 43
	v_readlane_b32 s46, v254, 44
	v_readlane_b32 s47, v254, 45
	v_readlane_b32 s48, v254, 46
	v_readlane_b32 s49, v254, 47
	v_readlane_b32 s50, v254, 48
	v_readlane_b32 s51, v254, 49
	v_readlane_b32 s52, v254, 50
	v_readlane_b32 s53, v254, 51
	v_readlane_b32 s54, v254, 52
	v_readlane_b32 s55, v254, 53
	global_load_dword v11, v[6:7], off
	v_add_u32_e32 v6, 16, v2
	v_ashrrev_i32_e32 v7, 31, v6
	v_lshlrev_b64 v[6:7], 12, v[6:7]
	v_lshl_add_u64 v[6:7], v[0:1], 0, v[6:7]
	global_load_dword v12, v[6:7], off
	v_add_u32_e32 v6, 24, v2
	v_ashrrev_i32_e32 v7, 31, v6
	v_lshlrev_b64 v[6:7], 12, v[6:7]
	v_lshl_add_u64 v[6:7], v[0:1], 0, v[6:7]
	global_load_dword v13, v[6:7], off
	v_add_u32_e32 v6, 32, v2
	v_ashrrev_i32_e32 v7, 31, v6
	v_lshlrev_b64 v[6:7], 12, v[6:7]
	v_lshl_add_u64 v[6:7], v[0:1], 0, v[6:7]
	global_load_dword v14, v[6:7], off
	v_add_u32_e32 v6, 40, v2
	v_ashrrev_i32_e32 v7, 31, v6
	v_lshlrev_b64 v[6:7], 12, v[6:7]
	v_lshl_add_u64 v[6:7], v[0:1], 0, v[6:7]
	global_load_dword v15, v[6:7], off
	v_add_u32_e32 v6, 48, v2
	v_ashrrev_i32_e32 v7, 31, v6
	v_lshlrev_b64 v[6:7], 12, v[6:7]
	v_lshl_add_u64 v[6:7], v[0:1], 0, v[6:7]
	v_add_u32_e32 v2, 56, v2
	global_load_dword v16, v[6:7], off
	v_ashrrev_i32_e32 v3, 31, v2
	v_lshlrev_b64 v[2:3], 12, v[2:3]
	v_lshl_add_u64 v[0:1], v[0:1], 0, v[2:3]
	global_load_dword v17, v[0:1], off
	s_waitcnt vmcnt(7)
	ds_write_b32 v4, v10
	s_waitcnt vmcnt(6)
	ds_write_b32 v4, v11 offset:2080
	s_waitcnt vmcnt(5)
	ds_write_b32 v4, v12 offset:4160
	s_waitcnt vmcnt(4)
	ds_write_b32 v4, v13 offset:6240
	s_waitcnt vmcnt(3)
	ds_write_b32 v4, v14 offset:8320
	s_waitcnt vmcnt(2)
	ds_write_b32 v4, v15 offset:10400
	s_waitcnt vmcnt(1)
	ds_write_b32 v4, v16 offset:12480
	s_waitcnt vmcnt(0)
	ds_write_b32 v4, v17 offset:14560
	v_lshlrev_b32_e32 v0, 3, v8
	v_and_b32_e32 v176, 56, v0
	v_mul_u32_u24_e32 v0, 0x104, v176
	v_lshl_add_u32 v4, v9, 2, v0
	s_waitcnt lgkmcnt(0)
	s_barrier
	ds_read2_b32 v[0:1], v4 offset1:65
	ds_read2_b32 v[2:3], v4 offset0:130 offset1:195
	v_add_u32_e32 v6, 0x400, v4
	ds_read2_b32 v[4:5], v6 offset0:4 offset1:69
	ds_read2_b32 v[6:7], v6 offset0:134 offset1:199
	s_waitcnt lgkmcnt(3)
	v_cvt_pk_bf16_f32 v0, v0, v1
	s_waitcnt lgkmcnt(2)
	v_cvt_pk_bf16_f32 v1, v2, v3
	s_waitcnt lgkmcnt(1)
	v_cvt_pk_bf16_f32 v2, v4, v5
	v_add_u32_e32 v4, s7, v9
	v_ashrrev_i32_e32 v5, 31, v4
	v_lshlrev_b64 v[4:5], 9, v[4:5]
	v_lshl_add_u64 v[4:5], s[4:5], 0, v[4:5]
	s_waitcnt lgkmcnt(0)
	v_cvt_pk_bf16_f32 v3, v6, v7
	v_lshl_add_u64 v[4:5], v[4:5], 0, s[36:37]

.LBB0_588:
	s_andn2_b64 vcc, exec, s[4:5]
	s_cbranch_vccnz .LBB0_573
	s_mul_hi_i32 s4, s10, 0x4bda12f7
	s_lshr_b32 s5, s4, 31
	s_ashr_i32 s4, s4, 9
	s_add_i32 s4, s4, s5
	v_readlane_b32 s40, v253, 12
	s_mul_i32 s6, s4, 0x1b00000
	v_readlane_b32 s46, v253, 18
	s_mul_hi_i32 s5, s4, 0x1b00000
	v_readlane_b32 s41, v253, 13
	v_readlane_b32 s42, v253, 14
	v_readlane_b32 s43, v253, 15
	v_readlane_b32 s44, v253, 16
	v_readlane_b32 s45, v253, 17
	v_readlane_b32 s47, v253, 19
	v_readlane_b32 s48, v253, 20
	v_readlane_b32 s49, v253, 21
	v_readlane_b32 s50, v253, 22
	v_readlane_b32 s51, v253, 23
	v_readlane_b32 s52, v253, 24
	v_readlane_b32 s53, v253, 25
	v_readlane_b32 s54, v253, 26
	v_readlane_b32 s55, v253, 27
	s_add_u32 s11, s46, s6
	s_addc_u32 s5, s47, s5
	v_readlane_b32 s40, v254, 1
	s_mul_i32 s6, s4, 0xd80000
	v_readlane_b32 s42, v254, 3
	s_mul_hi_i32 s7, s4, 0xd80000
	v_readlane_b32 s43, v254, 4
	s_add_u32 s6, s42, s6
	s_mulk_i32 s4, 0xf940
	s_addc_u32 s7, s43, s7
	s_add_i32 s4, s4, s10
	s_mul_hi_i32 s8, s4, 0x4bda12f7
	s_lshr_b32 s9, s8, 31
	s_ashr_i32 s8, s8, 5
	s_add_i32 s8, s8, s9
	s_mul_i32 s9, s8, 0xffffff94
	s_add_i32 s9, s9, s4
	s_lshl_b32 s4, s8, 6
	s_lshl_b32 s8, s9, 6
	s_ashr_i32 s9, s8, 31
	v_mov_b32_e32 v6, v190
	s_lshl_b64 s[12:13], s[8:9], 2
	s_add_u32 s12, s11, s12
	v_lshlrev_b32_e32 v0, 2, v6
	v_ashrrev_i32_e32 v4, 6, v6
	s_addc_u32 s13, s5, s13
	v_and_b32_e32 v176, 0xfc, v0
	v_lshl_add_u64 v[0:1], s[12:13], 0, v[176:177]
	v_add_u32_e32 v7, s4, v4
	v_mad_i64_i32 v[2:3], s[12:13], v7, s16, v[0:1]
	s_barrier
	global_load_dword v10, v[2:3], off
	v_mad_u64_u32 v[2:3], s[12:13], v4, s15, v[176:177]
	v_add_u32_e32 v3, 8, v7
	v_ashrrev_i32_e32 v8, 3, v6
	s_ashr_i32 s5, s4, 31
	v_readlane_b32 s41, v254, 2
	v_readlane_b32 s44, v254, 5
	v_readlane_b32 s45, v254, 6
	v_readlane_b32 s46, v254, 7
	v_readlane_b32 s47, v254, 8
	v_readlane_b32 s48, v254, 9
	v_readlane_b32 s49, v254, 10
	v_readlane_b32 s50, v254, 11
	v_readlane_b32 s51, v254, 12
	v_readlane_b32 s52, v254, 13
	v_readlane_b32 s53, v254, 14
	v_readlane_b32 s54, v254, 15
	v_readlane_b32 s55, v254, 16
	v_mad_i64_i32 v[4:5], s[12:13], v3, s16, v[0:1]
	global_load_dword v11, v[4:5], off
	v_add_u32_e32 v3, 16, v7
	v_mad_i64_i32 v[4:5], s[12:13], v3, s16, v[0:1]
	global_load_dword v12, v[4:5], off
	v_add_u32_e32 v3, 24, v7
	v_mad_i64_i32 v[4:5], s[12:13], v3, s16, v[0:1]
	global_load_dword v13, v[4:5], off
	v_add_u32_e32 v3, 32, v7
	v_mad_i64_i32 v[4:5], s[12:13], v3, s16, v[0:1]
	global_load_dword v14, v[4:5], off
	v_add_u32_e32 v3, 40, v7
	v_mad_i64_i32 v[4:5], s[12:13], v3, s16, v[0:1]
	global_load_dword v15, v[4:5], off
	v_add_u32_e32 v3, 48, v7
	v_mad_i64_i32 v[4:5], s[12:13], v3, s16, v[0:1]
	global_load_dword v16, v[4:5], off
	v_add_u32_e32 v3, 56, v7
	v_mad_i64_i32 v[0:1], s[12:13], v3, s16, v[0:1]
	global_load_dword v17, v[0:1], off
	s_waitcnt vmcnt(7)
	ds_write_b32 v2, v10
	s_waitcnt vmcnt(6)
	ds_write_b32 v2, v11 offset:2080
	s_waitcnt vmcnt(5)
	ds_write_b32 v2, v12 offset:4160
	s_waitcnt vmcnt(4)
	ds_write_b32 v2, v13 offset:6240
	s_waitcnt vmcnt(3)
	ds_write_b32 v2, v14 offset:8320
	s_waitcnt vmcnt(2)
	ds_write_b32 v2, v15 offset:10400
	s_waitcnt vmcnt(1)
	ds_write_b32 v2, v16 offset:12480
	s_waitcnt vmcnt(0)
	ds_write_b32 v2, v17 offset:14560
	v_lshlrev_b32_e32 v0, 3, v6
	v_and_b32_e32 v176, 56, v0
	v_mul_u32_u24_e32 v0, 0x104, v176
	v_lshl_add_u32 v4, v8, 2, v0
	s_waitcnt lgkmcnt(0)
	s_barrier
	ds_read2_b32 v[0:1], v4 offset1:65
	ds_read2_b32 v[2:3], v4 offset0:130 offset1:195
	v_add_u32_e32 v6, 0x400, v4
	ds_read2_b32 v[4:5], v6 offset0:4 offset1:69
	ds_read2_b32 v[6:7], v6 offset0:134 offset1:199
	s_waitcnt lgkmcnt(3)
	v_cvt_pk_bf16_f32 v0, v0, v1
	s_waitcnt lgkmcnt(2)
	v_cvt_pk_bf16_f32 v1, v2, v3
	s_waitcnt lgkmcnt(1)
	v_cvt_pk_bf16_f32 v2, v4, v5
	v_add_u32_e32 v4, s8, v8
	v_ashrrev_i32_e32 v5, 31, v4
	v_lshlrev_b64 v[4:5], 11, v[4:5]
	v_lshl_add_u64 v[4:5], s[6:7], 0, v[4:5]
	s_waitcnt lgkmcnt(0)
	v_cvt_pk_bf16_f32 v3, v6, v7
	v_lshl_add_u64 v[4:5], s[4:5], 1, v[4:5]
	s_branch .LBB0_573
